# GEMM K-loops: dropped the s_setprio 0/1 pair in the middle of each 32-MFMA section and the redundant second lgkmcnt(0)
# baseline (speedup 1.0000x reference)
; #define PG8_STAGE(bufoff, gbase, voff) do { _Pragma("unroll") for (int _i = 0; _i < 2; ++_i) \
;         __builtin_amdgcn_global_load_lds((const unsigned*)((const char*)(gbase) + (voff)[_i]), (LAS unsigned*)(lds + (bufoff) + ldsw + _i * 8192), 16, 0, 0); } while (0)
; #define PG8_LDA(dst, b, h) do { _Pragma("unroll") for (int m = 0; m < 4; ++m) _Pragma("unroll") for (int k = 0; k < 2; ++k) dst[m][k] = *(const LAS bf16x8*)(lds + PG8_SA(b, h) + aoff + m * 2048 + k * 1024); } while (0)
; #define PG8_LDB(dst, b, h) do { _Pragma("unroll") for (int n = 0; n < 2; ++n) _Pragma("unroll") for (int k = 0; k < 2; ++k) dst[n][k] = *(const LAS bf16x8*)(lds + PG8_SB(b, h) + boff + n * 2048 + k * 1024); } while (0)
; #define PG8_MMA(ai, bj, At, Bt) do { __builtin_amdgcn_s_setprio(1); _Pragma("unroll") for (int m = 0; m < 4; ++m) _Pragma("unroll") for (int n = 0; n < 2; ++n) _Pragma("unroll") for (int k = 0; k < 2; ++k) \
;         acc[ai][bj][m][n] = __builtin_amdgcn_mfma_f32_16x16x32_bf16(Bt[n][k], At[m][k], acc[ai][bj][m][n], 0, 0, 0); __builtin_amdgcn_s_setprio(0); } while (0)
; #define PG8_WAIT_V(n) asm volatile("s_waitcnt vmcnt(" #n ")" ::: "memory")
; #define PG8_WAIT_L(n) asm volatile("s_waitcnt lgkmcnt(" #n ")" ::: "memory")
; #define PG8_BAR __builtin_amdgcn_s_barrier()
; #define PG8_SCHED __builtin_amdgcn_sched_barrier(0)
; template <class Epi>
; __device__ __forceinline__ void gemm_phase(LAS unsigned char* lds, const Gemm g, const int G, const int cidx, const Epi& E) {
;     ...
;             const char* a1 = cA + (size_t)(t + 1) * kstep;
;             const char* a2 = last ? nA : cA + (size_t)(t + 2) * kstep; const char* b2 = last ? nB : cB + (size_t)(t + 2) * kstep;
;             const char* a3 = a2 + kstep; const char* b3 = b2 + kstep;
;             PG8_LDB(B0, 0, 0); PG8_LDB(B1, 0, 1); PG8_SCHED; PG8_LDA(At, 0, 0); PG8_STAGE(PG8_SA(1, 1), a1 + hstep, voffA);
;             PG8_WAIT_V(8); PG8_WAIT_L(0); PG8_BAR; PG8_MMA(0, 0, At, B0); PG8_MMA(0, 1, At, B1); PG8_BAR; PG8_SCHED;
;             PG8_LDA(At, 0, 1); PG8_STAGE(PG8_SB(0, 0), b2, voffB); PG8_STAGE(PG8_SB(0, 1), b2 + hstep, voffB); PG8_STAGE(PG8_SA(0, 0), a2, voffA);
.LBB0_82:
	s_add_u32 s26, s24, 0xfffc0080
	s_addc_u32 s27, s25, -1
	s_add_i32 s43, 0, 0x10000
	s_cmp_eq_u32 s45, 12
	s_cselect_b32 s29, s13, s27
	s_cselect_b32 s28, s17, s26
	s_cselect_b32 s27, s9, s44
	s_cselect_b32 s26, s22, s33
	s_add_i32 s68, 0, 0x14000
	v_add_u32_e32 v162, s43, v145
	v_add_u32_e32 v178, s68, v145
	ds_read_b128 v[132:135], v162
	ds_read_b128 v[140:143], v162 offset:1024
	ds_read_b128 v[156:159], v162 offset:2048
	ds_read_b128 v[162:165], v162 offset:3072
	ds_read_b128 v[166:169], v178
	ds_read_b128 v[170:173], v178 offset:1024
	ds_read_b128 v[174:177], v178 offset:2048
	ds_read_b128 v[178:181], v178 offset:3072
	v_lshl_add_u64 v[226:227], s[24:25], 0, v[154:155]
	s_add_i32 m0, s21, 0xc000
	ds_read_b128 v[182:185], v161
	ds_read_b128 v[186:189], v161 offset:1024
	ds_read_b128 v[190:193], v161 offset:2048
	ds_read_b128 v[194:197], v161 offset:3072
	ds_read_b128 v[198:201], v161 offset:4096
	ds_read_b128 v[214:217], v161 offset:5120
	ds_read_b128 v[218:221], v161 offset:6144
	ds_read_b128 v[222:225], v161 offset:7168
	global_load_lds_dwordx4 v[226:227], off
	v_lshl_add_u64 v[226:227], s[24:25], 0, v[152:153]
	s_add_i32 m0, s21, 0xe000
	s_nop 0
	global_load_lds_dwordx4 v[226:227], off
	s_waitcnt vmcnt(8)
	s_waitcnt lgkmcnt(0)
	s_barrier
	s_setprio 1
	v_mfma_f32_16x16x32_bf16 v[128:131], v[132:135], v[182:185], v[128:131]
	v_mfma_f32_16x16x32_bf16 v[120:123], v[156:159], v[182:185], v[120:123]
	v_mfma_f32_16x16x32_bf16 v[112:115], v[132:135], v[190:193], v[112:115]
	v_mfma_f32_16x16x32_bf16 v[104:107], v[156:159], v[190:193], v[104:107]
	v_mfma_f32_16x16x32_bf16 v[96:99], v[132:135], v[198:201], v[96:99]
	v_mfma_f32_16x16x32_bf16 v[88:91], v[156:159], v[198:201], v[88:91]
	v_mfma_f32_16x16x32_bf16 v[80:83], v[132:135], v[218:221], v[80:83]
	v_mfma_f32_16x16x32_bf16 v[72:75], v[156:159], v[218:221], v[72:75]
	v_mfma_f32_16x16x32_bf16 v[128:131], v[140:143], v[186:189], v[128:131]
	v_mfma_f32_16x16x32_bf16 v[120:123], v[162:165], v[186:189], v[120:123]
	v_mfma_f32_16x16x32_bf16 v[112:115], v[140:143], v[194:197], v[112:115]
	v_mfma_f32_16x16x32_bf16 v[104:107], v[162:165], v[194:197], v[104:107]
	v_mfma_f32_16x16x32_bf16 v[96:99], v[140:143], v[214:217], v[96:99]
	v_mfma_f32_16x16x32_bf16 v[88:91], v[162:165], v[214:217], v[88:91]
	v_mfma_f32_16x16x32_bf16 v[80:83], v[140:143], v[222:225], v[80:83]
	v_mfma_f32_16x16x32_bf16 v[72:75], v[162:165], v[222:225], v[72:75]
	v_mfma_f32_16x16x32_bf16 v[124:127], v[166:169], v[182:185], v[124:127]
	v_mfma_f32_16x16x32_bf16 v[116:119], v[174:177], v[182:185], v[116:119]
	v_mfma_f32_16x16x32_bf16 v[108:111], v[166:169], v[190:193], v[108:111]
	v_mfma_f32_16x16x32_bf16 v[100:103], v[174:177], v[190:193], v[100:103]
	v_mfma_f32_16x16x32_bf16 v[92:95], v[166:169], v[198:201], v[92:95]
	v_mfma_f32_16x16x32_bf16 v[84:87], v[174:177], v[198:201], v[84:87]
	v_mfma_f32_16x16x32_bf16 v[76:79], v[166:169], v[218:221], v[76:79]
	v_mfma_f32_16x16x32_bf16 v[68:71], v[174:177], v[218:221], v[68:71]
	v_mfma_f32_16x16x32_bf16 v[124:127], v[170:173], v[186:189], v[124:127]
	v_mfma_f32_16x16x32_bf16 v[116:119], v[178:181], v[186:189], v[116:119]
	v_mfma_f32_16x16x32_bf16 v[108:111], v[170:173], v[194:197], v[108:111]
	v_mfma_f32_16x16x32_bf16 v[100:103], v[178:181], v[194:197], v[100:103]
	v_mfma_f32_16x16x32_bf16 v[92:95], v[170:173], v[214:217], v[92:95]
	v_mfma_f32_16x16x32_bf16 v[84:87], v[178:181], v[214:217], v[84:87]
	v_mfma_f32_16x16x32_bf16 v[76:79], v[170:173], v[222:225], v[76:79]
	v_mfma_f32_16x16x32_bf16 v[68:71], v[178:181], v[222:225], v[68:71]
	s_setprio 0
	s_barrier
	s_add_i32 s43, s43, s36
	v_lshl_add_u64 v[226:227], s[26:27], 0, v[148:149]
	s_mov_b32 m0, s43
	ds_read_b128 v[182:185], v161 offset:16384
	ds_read_b128 v[186:189], v161 offset:17408
	ds_read_b128 v[190:193], v161 offset:18432
	ds_read_b128 v[194:197], v161 offset:19456
	ds_read_b128 v[198:201], v161 offset:20480
	ds_read_b128 v[214:217], v161 offset:21504
	ds_read_b128 v[218:221], v161 offset:22528
	ds_read_b128 v[222:225], v161 offset:23552
	global_load_lds_dwordx4 v[226:227], off
	s_add_i32 m0, s43, 0x2000
	s_add_u32 s76, s26, 0x40000
	v_lshl_add_u64 v[228:229], s[26:27], 0, v[0:1]
	s_addc_u32 s77, s27, 0
	s_add_i32 s43, s68, s36
	global_load_lds_dwordx4 v[228:229], off
	v_lshl_add_u64 v[230:231], s[76:77], 0, v[148:149]
	s_mov_b32 m0, s43
	v_lshl_add_u64 v[232:233], s[28:29], 0, v[146:147]
	global_load_lds_dwordx4 v[230:231], off
	v_lshl_add_u64 v[230:231], s[76:77], 0, v[0:1]
	s_add_i32 m0, s43, 0x2000
	s_nop 0
	global_load_lds_dwordx4 v[230:231], off
	v_lshl_add_u64 v[230:231], s[28:29], 0, v[150:151]
	s_mov_b32 m0, s21
	s_nop 0
	global_load_lds_dwordx4 v[230:231], off
	s_mov_b32 m0, s38
	s_nop 0
	global_load_lds_dwordx4 v[232:233], off
	s_waitcnt vmcnt(8)
	s_waitcnt lgkmcnt(0)
	s_barrier
; #define PG8_STAGE(bufoff, gbase, voff) do { _Pragma("unroll") for (int _i = 0; _i < 2; ++_i) \
;         __builtin_amdgcn_global_load_lds((const unsigned*)((const char*)(gbase) + (voff)[_i]), (LAS unsigned*)(lds + (bufoff) + ldsw + _i * 8192), 16, 0, 0); } while (0)
; #define PG8_LDA(dst, b, h) do { _Pragma("unroll") for (int m = 0; m < 4; ++m) _Pragma("unroll") for (int k = 0; k < 2; ++k) dst[m][k] = *(const LAS bf16x8*)(lds + PG8_SA(b, h) + aoff + m * 2048 + k * 1024); } while (0)
; #define PG8_LDB(dst, b, h) do { _Pragma("unroll") for (int n = 0; n < 2; ++n) _Pragma("unroll") for (int k = 0; k < 2; ++k) dst[n][k] = *(const LAS bf16x8*)(lds + PG8_SB(b, h) + boff + n * 2048 + k * 1024); } while (0)
; #define PG8_MMA(ai, bj, At, Bt) do { __builtin_amdgcn_s_setprio(1); _Pragma("unroll") for (int m = 0; m < 4; ++m) _Pragma("unroll") for (int n = 0; n < 2; ++n) _Pragma("unroll") for (int k = 0; k < 2; ++k) \
;         acc[ai][bj][m][n] = __builtin_amdgcn_mfma_f32_16x16x32_bf16(Bt[n][k], At[m][k], acc[ai][bj][m][n], 0, 0, 0); __builtin_amdgcn_s_setprio(0); } while (0)
; #define PG8_WAIT_V(n) asm volatile("s_waitcnt vmcnt(" #n ")" ::: "memory")
; #define PG8_WAIT_L(n) asm volatile("s_waitcnt lgkmcnt(" #n ")" ::: "memory")
; #define PG8_BAR __builtin_amdgcn_s_barrier()
; #define PG8_SCHED __builtin_amdgcn_sched_barrier(0)
; template <class Epi>
; __device__ __forceinline__ void gemm_phase(LAS unsigned char* lds, const Gemm g, const int G, const int cidx, const Epi& E) {
;     ...
;             PG8_WAIT_V(8); PG8_WAIT_L(0); PG8_BAR; PG8_MMA(1, 0, At, B0); PG8_MMA(1, 1, At, B1); PG8_BAR; PG8_SCHED;
;             PG8_LDB(B0, 1, 0); PG8_LDB(B1, 1, 1); PG8_SCHED; PG8_LDA(At, 1, 0); PG8_STAGE(PG8_SA(0, 1), a2 + hstep, voffA);
;             PG8_WAIT_V(8); PG8_WAIT_L(0); PG8_BAR; PG8_MMA(0, 0, At, B0); PG8_MMA(0, 1, At, B1); PG8_BAR; PG8_SCHED;
	s_setprio 1
	v_mfma_f32_16x16x32_bf16 v[64:67], v[132:135], v[182:185], v[64:67]
	v_mfma_f32_16x16x32_bf16 v[56:59], v[156:159], v[182:185], v[56:59]
	v_mfma_f32_16x16x32_bf16 v[48:51], v[132:135], v[190:193], v[48:51]
	v_mfma_f32_16x16x32_bf16 v[40:43], v[156:159], v[190:193], v[40:43]
	v_mfma_f32_16x16x32_bf16 v[32:35], v[132:135], v[198:201], v[32:35]
	v_mfma_f32_16x16x32_bf16 v[24:27], v[156:159], v[198:201], v[24:27]
	v_mfma_f32_16x16x32_bf16 v[16:19], v[132:135], v[218:221], v[16:19]
	v_mfma_f32_16x16x32_bf16 v[8:11], v[156:159], v[218:221], v[8:11]
	v_mfma_f32_16x16x32_bf16 v[64:67], v[140:143], v[186:189], v[64:67]
	v_mfma_f32_16x16x32_bf16 v[56:59], v[162:165], v[186:189], v[56:59]
	v_mfma_f32_16x16x32_bf16 v[48:51], v[140:143], v[194:197], v[48:51]
	v_mfma_f32_16x16x32_bf16 v[40:43], v[162:165], v[194:197], v[40:43]
	v_mfma_f32_16x16x32_bf16 v[32:35], v[140:143], v[214:217], v[32:35]
	v_mfma_f32_16x16x32_bf16 v[24:27], v[162:165], v[214:217], v[24:27]
	v_mfma_f32_16x16x32_bf16 v[16:19], v[140:143], v[222:225], v[16:19]
	v_mfma_f32_16x16x32_bf16 v[8:11], v[162:165], v[222:225], v[8:11]
	v_mfma_f32_16x16x32_bf16 v[60:63], v[166:169], v[182:185], v[60:63]
	v_mfma_f32_16x16x32_bf16 v[52:55], v[174:177], v[182:185], v[52:55]
	v_mfma_f32_16x16x32_bf16 v[44:47], v[166:169], v[190:193], v[44:47]
	v_mfma_f32_16x16x32_bf16 v[36:39], v[174:177], v[190:193], v[36:39]
	v_mfma_f32_16x16x32_bf16 v[28:31], v[166:169], v[198:201], v[28:31]
	v_mfma_f32_16x16x32_bf16 v[20:23], v[174:177], v[198:201], v[20:23]
	v_mfma_f32_16x16x32_bf16 v[12:15], v[166:169], v[218:221], v[12:15]
	v_mfma_f32_16x16x32_bf16 v[4:7], v[174:177], v[218:221], v[4:7]
	v_mfma_f32_16x16x32_bf16 v[60:63], v[170:173], v[186:189], v[60:63]
	v_mfma_f32_16x16x32_bf16 v[52:55], v[178:181], v[186:189], v[52:55]
	v_mfma_f32_16x16x32_bf16 v[44:47], v[170:173], v[194:197], v[44:47]
	v_mfma_f32_16x16x32_bf16 v[36:39], v[178:181], v[194:197], v[36:39]
	v_mfma_f32_16x16x32_bf16 v[28:31], v[170:173], v[214:217], v[28:31]
	v_mfma_f32_16x16x32_bf16 v[20:23], v[178:181], v[214:217], v[20:23]
	v_mfma_f32_16x16x32_bf16 v[12:15], v[170:173], v[222:225], v[12:15]
	v_mfma_f32_16x16x32_bf16 v[4:7], v[178:181], v[222:225], v[4:7]
	s_setprio 0
	s_barrier
	s_add_i32 s43, 0, 0x18000
	s_add_i32 s68, 0, 0x1c000
	v_add_u32_e32 v162, s43, v145
	v_add_u32_e32 v178, s68, v145
	ds_read_b128 v[132:135], v162
	ds_read_b128 v[140:143], v162 offset:1024
	ds_read_b128 v[156:159], v162 offset:2048
	ds_read_b128 v[162:165], v162 offset:3072
	ds_read_b128 v[166:169], v178
	ds_read_b128 v[170:173], v178 offset:1024
	ds_read_b128 v[174:177], v178 offset:2048
	ds_read_b128 v[178:181], v178 offset:3072
	s_add_u32 s28, s28, 0x40000
	s_addc_u32 s29, s29, 0
	s_mov_b32 m0, s39
	v_lshl_add_u64 v[234:235], s[28:29], 0, v[150:151]
	ds_read_b128 v[182:185], v161 offset:32768
	ds_read_b128 v[186:189], v161 offset:33792
	ds_read_b128 v[190:193], v161 offset:34816
	ds_read_b128 v[194:197], v161 offset:35840
	ds_read_b128 v[198:201], v161 offset:36864
	ds_read_b128 v[214:217], v161 offset:37888
	ds_read_b128 v[218:221], v161 offset:38912
	ds_read_b128 v[222:225], v161 offset:39936
	global_load_lds_dwordx4 v[234:235], off
	v_lshl_add_u64 v[234:235], s[28:29], 0, v[146:147]
	s_mov_b32 m0, s75
	s_nop 0
	global_load_lds_dwordx4 v[234:235], off
	s_waitcnt vmcnt(8)
	s_waitcnt lgkmcnt(0)
	s_barrier
	s_setprio 1
	v_mfma_f32_16x16x32_bf16 v[128:131], v[132:135], v[182:185], v[128:131]
	v_mfma_f32_16x16x32_bf16 v[120:123], v[156:159], v[182:185], v[120:123]
	v_mfma_f32_16x16x32_bf16 v[112:115], v[132:135], v[190:193], v[112:115]
	v_mfma_f32_16x16x32_bf16 v[104:107], v[156:159], v[190:193], v[104:107]
	v_mfma_f32_16x16x32_bf16 v[96:99], v[132:135], v[198:201], v[96:99]
	v_mfma_f32_16x16x32_bf16 v[88:91], v[156:159], v[198:201], v[88:91]
	v_mfma_f32_16x16x32_bf16 v[80:83], v[132:135], v[218:221], v[80:83]
	v_mfma_f32_16x16x32_bf16 v[72:75], v[156:159], v[218:221], v[72:75]
	v_mfma_f32_16x16x32_bf16 v[128:131], v[140:143], v[186:189], v[128:131]
	v_mfma_f32_16x16x32_bf16 v[120:123], v[162:165], v[186:189], v[120:123]
	v_mfma_f32_16x16x32_bf16 v[112:115], v[140:143], v[194:197], v[112:115]
	v_mfma_f32_16x16x32_bf16 v[104:107], v[162:165], v[194:197], v[104:107]
	v_mfma_f32_16x16x32_bf16 v[96:99], v[140:143], v[214:217], v[96:99]
	v_mfma_f32_16x16x32_bf16 v[88:91], v[162:165], v[214:217], v[88:91]
	v_mfma_f32_16x16x32_bf16 v[80:83], v[140:143], v[222:225], v[80:83]
	v_mfma_f32_16x16x32_bf16 v[72:75], v[162:165], v[222:225], v[72:75]
	v_mfma_f32_16x16x32_bf16 v[124:127], v[166:169], v[182:185], v[124:127]
	v_mfma_f32_16x16x32_bf16 v[116:119], v[174:177], v[182:185], v[116:119]
	v_mfma_f32_16x16x32_bf16 v[108:111], v[166:169], v[190:193], v[108:111]
	v_mfma_f32_16x16x32_bf16 v[100:103], v[174:177], v[190:193], v[100:103]
	v_mfma_f32_16x16x32_bf16 v[92:95], v[166:169], v[198:201], v[92:95]
	v_mfma_f32_16x16x32_bf16 v[84:87], v[174:177], v[198:201], v[84:87]
	v_mfma_f32_16x16x32_bf16 v[76:79], v[166:169], v[218:221], v[76:79]
	v_mfma_f32_16x16x32_bf16 v[68:71], v[174:177], v[218:221], v[68:71]
	v_mfma_f32_16x16x32_bf16 v[124:127], v[170:173], v[186:189], v[124:127]
	v_mfma_f32_16x16x32_bf16 v[116:119], v[178:181], v[186:189], v[116:119]
	v_mfma_f32_16x16x32_bf16 v[108:111], v[170:173], v[194:197], v[108:111]
	v_mfma_f32_16x16x32_bf16 v[100:103], v[178:181], v[194:197], v[100:103]
	v_mfma_f32_16x16x32_bf16 v[92:95], v[170:173], v[214:217], v[92:95]
	v_mfma_f32_16x16x32_bf16 v[84:87], v[178:181], v[214:217], v[84:87]
	v_mfma_f32_16x16x32_bf16 v[76:79], v[170:173], v[222:225], v[76:79]
	v_mfma_f32_16x16x32_bf16 v[68:71], v[178:181], v[222:225], v[68:71]
	s_setprio 0
	s_barrier
; __device__ __forceinline__ unsigned pk2(float lo, float hi) { unsigned r; asm("v_cvt_pk_bf16_f32 %0, %1, %2" : "=v"(r) : "v"(lo), "v"(hi)); return r; }
; __device__ __forceinline__ float silu(float x) { return x * sigm(x); }
; #define PG8_STAGE(bufoff, gbase, voff) do { _Pragma("unroll") for (int _i = 0; _i < 2; ++_i) \
;         __builtin_amdgcn_global_load_lds((const unsigned*)((const char*)(gbase) + (voff)[_i]), (LAS unsigned*)(lds + (bufoff) + ldsw + _i * 8192), 16, 0, 0); } while (0)
; #define PG8_LDA(dst, b, h) do { _Pragma("unroll") for (int m = 0; m < 4; ++m) _Pragma("unroll") for (int k = 0; k < 2; ++k) dst[m][k] = *(const LAS bf16x8*)(lds + PG8_SA(b, h) + aoff + m * 2048 + k * 1024); } while (0)
; #define PG8_MMA(ai, bj, At, Bt) do { __builtin_amdgcn_s_setprio(1); _Pragma("unroll") for (int m = 0; m < 4; ++m) _Pragma("unroll") for (int n = 0; n < 2; ++n) _Pragma("unroll") for (int k = 0; k < 2; ++k) \
;         acc[ai][bj][m][n] = __builtin_amdgcn_mfma_f32_16x16x32_bf16(Bt[n][k], At[m][k], acc[ai][bj][m][n], 0, 0, 0); __builtin_amdgcn_s_setprio(0); } while (0)
;     __device__ __forceinline__ void operator()(const f32x4 (&acc)[2][2][4][2], const Unit& u, int wr, int wc, int fr, int fq) const {
;         const int row0 = u.pm * BM + wr * 64 + fr, col0 = u.pn * HALF + wc * 32 + 8 * fq;
; #pragma unroll
;         for (int ai = 0; ai < 2; ++ai)
; #pragma unroll
;             for (int m = 0; m < 4; ++m) { bf16_t* rowp = O + (size_t)(row0 + ai * HALF + m * 16) * ldc + col0;
;                 const f32x4 g0 = acc[ai][0][m][0], g1 = acc[ai][0][m][1], u0 = acc[ai][1][m][0], u1 = acc[ai][1][m][1];
;                 u32x4 w; w.x = pk2(silu(g0[0]) * u0[0], silu(g0[1]) * u0[1]); w.y = pk2(silu(g0[2]) * u0[2], silu(g0[3]) * u0[3]);
;                 w.z = pk2(silu(g1[0]) * u1[0], silu(g1[1]) * u1[1]); w.w = pk2(silu(g1[2]) * u1[2], silu(g1[3]) * u1[3]);
;                 *(u32x4*)rowp = w; }
; template <class Epi>
; __device__ __forceinline__ void gemm_phase(LAS unsigned char* lds, const Gemm g, const int G, const int cidx, const Epi& E) {
;     ...
;             PG8_LDA(At, 1, 1); PG8_STAGE(PG8_SB(1, 0), b3, voffB); PG8_STAGE(PG8_SB(1, 1), b3 + hstep, voffB); PG8_STAGE(PG8_SA(1, 0), a3, voffA);
;             PG8_WAIT_V(8); PG8_WAIT_L(0); PG8_BAR; PG8_MMA(1, 0, At, B0); PG8_MMA(1, 1, At, B1); PG8_BAR; PG8_SCHED;
;         }
	s_add_i32 s28, s43, s36
	v_lshl_add_u64 v[226:227], v[226:227], 0, s[46:47]
	s_mov_b32 m0, s28
	ds_read_b128 v[182:185], v161 offset:49152
	ds_read_b128 v[186:189], v161 offset:50176
	ds_read_b128 v[190:193], v161 offset:51200
	ds_read_b128 v[194:197], v161 offset:52224
	ds_read_b128 v[198:201], v161 offset:53248
	ds_read_b128 v[214:217], v161 offset:54272
	ds_read_b128 v[218:221], v161 offset:55296
	ds_read_b128 v[222:225], v161 offset:56320
	global_load_lds_dwordx4 v[226:227], off
	s_add_i32 m0, s28, 0x2000
	s_add_u32 s26, s26, 0x40080
	v_lshl_add_u64 v[226:227], v[228:229], 0, s[46:47]
	s_addc_u32 s27, s27, 0
	s_add_i32 s28, s68, s36
	global_load_lds_dwordx4 v[226:227], off
	v_lshl_add_u64 v[226:227], s[26:27], 0, v[148:149]
	s_mov_b32 m0, s28
	s_nop 0
	global_load_lds_dwordx4 v[226:227], off
	v_lshl_add_u64 v[226:227], s[26:27], 0, v[0:1]
	s_add_i32 m0, s28, 0x2000
	s_nop 0
	global_load_lds_dwordx4 v[226:227], off
	v_lshl_add_u64 v[226:227], v[230:231], 0, s[46:47]
	s_mov_b32 m0, s79
	s_nop 0
	global_load_lds_dwordx4 v[226:227], off
	v_lshl_add_u64 v[226:227], v[232:233], 0, s[46:47]
	s_mov_b32 m0, s34
	s_nop 0
	global_load_lds_dwordx4 v[226:227], off
	s_waitcnt vmcnt(8)
	s_waitcnt lgkmcnt(0)
	s_barrier
	s_setprio 1
	v_mfma_f32_16x16x32_bf16 v[64:67], v[132:135], v[182:185], v[64:67]
	v_mfma_f32_16x16x32_bf16 v[56:59], v[156:159], v[182:185], v[56:59]
	v_mfma_f32_16x16x32_bf16 v[48:51], v[132:135], v[190:193], v[48:51]
	v_mfma_f32_16x16x32_bf16 v[40:43], v[156:159], v[190:193], v[40:43]
	v_mfma_f32_16x16x32_bf16 v[32:35], v[132:135], v[198:201], v[32:35]
	v_mfma_f32_16x16x32_bf16 v[24:27], v[156:159], v[198:201], v[24:27]
	v_mfma_f32_16x16x32_bf16 v[16:19], v[132:135], v[218:221], v[16:19]
	v_mfma_f32_16x16x32_bf16 v[8:11], v[156:159], v[218:221], v[8:11]
	v_mfma_f32_16x16x32_bf16 v[64:67], v[140:143], v[186:189], v[64:67]
	v_mfma_f32_16x16x32_bf16 v[56:59], v[162:165], v[186:189], v[56:59]
	v_mfma_f32_16x16x32_bf16 v[48:51], v[140:143], v[194:197], v[48:51]
	v_mfma_f32_16x16x32_bf16 v[40:43], v[162:165], v[194:197], v[40:43]
	v_mfma_f32_16x16x32_bf16 v[32:35], v[140:143], v[214:217], v[32:35]
	v_mfma_f32_16x16x32_bf16 v[24:27], v[162:165], v[214:217], v[24:27]
	v_mfma_f32_16x16x32_bf16 v[16:19], v[140:143], v[222:225], v[16:19]
	v_mfma_f32_16x16x32_bf16 v[8:11], v[162:165], v[222:225], v[8:11]
	v_mfma_f32_16x16x32_bf16 v[60:63], v[166:169], v[182:185], v[60:63]
	v_mfma_f32_16x16x32_bf16 v[52:55], v[174:177], v[182:185], v[52:55]
	v_mfma_f32_16x16x32_bf16 v[44:47], v[166:169], v[190:193], v[44:47]
	v_mfma_f32_16x16x32_bf16 v[36:39], v[174:177], v[190:193], v[36:39]
	v_mfma_f32_16x16x32_bf16 v[28:31], v[166:169], v[198:201], v[28:31]
	v_mfma_f32_16x16x32_bf16 v[20:23], v[174:177], v[198:201], v[20:23]
	v_mfma_f32_16x16x32_bf16 v[12:15], v[166:169], v[218:221], v[12:15]
	v_mfma_f32_16x16x32_bf16 v[4:7], v[174:177], v[218:221], v[4:7]
	v_mfma_f32_16x16x32_bf16 v[60:63], v[170:173], v[186:189], v[60:63]
	v_mfma_f32_16x16x32_bf16 v[52:55], v[178:181], v[186:189], v[52:55]
	v_mfma_f32_16x16x32_bf16 v[44:47], v[170:173], v[194:197], v[44:47]
	v_mfma_f32_16x16x32_bf16 v[36:39], v[178:181], v[194:197], v[36:39]
	v_mfma_f32_16x16x32_bf16 v[28:31], v[170:173], v[214:217], v[28:31]
	v_mfma_f32_16x16x32_bf16 v[20:23], v[178:181], v[214:217], v[20:23]
	v_mfma_f32_16x16x32_bf16 v[12:15], v[170:173], v[222:225], v[12:15]
	v_mfma_f32_16x16x32_bf16 v[4:7], v[178:181], v[222:225], v[4:7]
	s_setprio 0
	s_barrier
	s_add_i32 s45, s45, 2
	s_add_u32 s33, s33, 0x100
	s_addc_u32 s44, s44, 0
	s_add_u32 s24, s24, 0x100
	s_addc_u32 s25, s25, 0
	s_cmp_gt_u32 s45, 13
	s_cbranch_scc0 .LBB0_82
	v_lshl_or_b32 v132, s16, 7, v160
	v_lshl_add_u32 v162, s20, 8, v3
	v_ashrrev_i32_e32 v133, 31, v132
	v_mov_b64_e32 v[156:157], s[6:7]
	s_movk_i32 s9, 0x1600
	v_mad_i64_i32 v[134:135], s[16:17], v162, s9, v[156:157]
	v_lshlrev_b64 v[158:159], 1, v[132:133]
	v_lshl_add_u64 v[132:133], v[134:135], 0, v[158:159]
	v_mul_f32_e32 v134, 0xbfb8aa3b, v128
	v_exp_f32_e32 v134, v134
	s_and_b64 vcc, exec, s[4:5]
	s_mov_b32 s20, s12
	s_mov_b64 s[24:25], s[18:19]
	v_add_f32_e32 v134, 1.0, v134
	v_rcp_f32_e32 v134, v134
	s_mov_b64 s[26:27], s[14:15]
	v_mul_f32_e32 v128, v128, v134
	v_mul_f32_e32 v124, v128, v124
	v_mul_f32_e32 v128, 0xbfb8aa3b, v129
	v_exp_f32_e32 v128, v128
	s_nop 0
	v_add_f32_e32 v128, 1.0, v128
	v_rcp_f32_e32 v128, v128
	s_nop 0
	v_mul_f32_e32 v128, v129, v128
	v_mul_f32_e32 v125, v128, v125
	v_cvt_pk_bf16_f32 v124, v124, v125
	v_mul_f32_e32 v125, 0xbfb8aa3b, v130
	v_exp_f32_e32 v125, v125
	s_nop 0
	v_add_f32_e32 v125, 1.0, v125
	v_rcp_f32_e32 v125, v125
	s_nop 0
	v_mul_f32_e32 v125, v130, v125
	v_mul_f32_e32 v125, v125, v126
	v_mul_f32_e32 v126, 0xbfb8aa3b, v131
	v_exp_f32_e32 v126, v126
	s_nop 0
	v_add_f32_e32 v126, 1.0, v126
	v_rcp_f32_e32 v126, v126
	s_nop 0
	v_mul_f32_e32 v126, v131, v126
	v_mul_f32_e32 v126, v126, v127
	v_cvt_pk_bf16_f32 v125, v125, v126
	v_mul_f32_e32 v126, 0xbfb8aa3b, v120
	v_exp_f32_e32 v126, v126
	s_nop 0
	v_add_f32_e32 v126, 1.0, v126
	v_rcp_f32_e32 v126, v126
	s_nop 0
	v_mul_f32_e32 v120, v120, v126
	v_mul_f32_e32 v116, v120, v116
	v_mul_f32_e32 v120, 0xbfb8aa3b, v121
	v_exp_f32_e32 v120, v120
	s_nop 0
	v_add_f32_e32 v120, 1.0, v120
	v_rcp_f32_e32 v120, v120
	s_nop 0
	v_mul_f32_e32 v120, v121, v120
	v_mul_f32_e32 v117, v120, v117
	v_cvt_pk_bf16_f32 v126, v116, v117
	v_mul_f32_e32 v116, 0xbfb8aa3b, v122
	v_exp_f32_e32 v116, v116
	v_mul_f32_e32 v117, 0xbfb8aa3b, v123
	v_exp_f32_e32 v117, v117
	v_add_f32_e32 v116, 1.0, v116
	v_rcp_f32_e32 v116, v116
	v_add_f32_e32 v117, 1.0, v117
	v_rcp_f32_e32 v117, v117
	v_mul_f32_e32 v116, v122, v116
; __device__ __forceinline__ unsigned pk2(float lo, float hi) { unsigned r; asm("v_cvt_pk_bf16_f32 %0, %1, %2" : "=v"(r) : "v"(lo), "v"(hi)); return r; }
; __device__ __forceinline__ float silu(float x) { return x * sigm(x); }
;     __device__ __forceinline__ void operator()(const f32x4 (&acc)[2][2][4][2], const Unit& u, int wr, int wc, int fr, int fq) const {
;     ...
;             for (int m = 0; m < 4; ++m) { bf16_t* rowp = O + (size_t)(row0 + ai * HALF + m * 16) * ldc + col0;
;                 const f32x4 g0 = acc[ai][0][m][0], g1 = acc[ai][0][m][1], u0 = acc[ai][1][m][0], u1 = acc[ai][1][m][1];
;                 u32x4 w; w.x = pk2(silu(g0[0]) * u0[0], silu(g0[1]) * u0[1]); w.y = pk2(silu(g0[2]) * u0[2], silu(g0[3]) * u0[3]);
;                 w.z = pk2(silu(g1[0]) * u1[0], silu(g1[1]) * u1[1]); w.w = pk2(silu(g1[2]) * u1[2], silu(g1[3]) * u1[3]);
;                 *(u32x4*)rowp = w; }
	v_mul_f32_e32 v116, v116, v118
	v_mul_f32_e32 v118, 0xbfb8aa3b, v112
	v_exp_f32_e32 v118, v118
	v_mul_f32_e32 v117, v123, v117
	v_mul_f32_e32 v117, v117, v119
	v_cvt_pk_bf16_f32 v127, v116, v117
	v_add_f32_e32 v118, 1.0, v118
	v_rcp_f32_e32 v118, v118
	v_or_b32_e32 v116, 16, v162
	v_mad_i64_i32 v[116:117], s[16:17], v116, s9, v[156:157]
	v_mul_f32_e32 v112, v112, v118
	v_mul_f32_e32 v108, v112, v108
	v_mul_f32_e32 v112, 0xbfb8aa3b, v113
	v_exp_f32_e32 v112, v112
	v_lshl_add_u64 v[116:117], v[116:117], 0, v[158:159]
	global_store_dwordx4 v[132:133], v[124:127], off
	v_add_f32_e32 v112, 1.0, v112
	v_rcp_f32_e32 v112, v112
	s_nop 0
	v_mul_f32_e32 v112, v113, v112
	v_mul_f32_e32 v109, v112, v109
	v_cvt_pk_bf16_f32 v108, v108, v109
	v_mul_f32_e32 v109, 0xbfb8aa3b, v114
	v_exp_f32_e32 v109, v109
	s_nop 0
	v_add_f32_e32 v109, 1.0, v109
	v_rcp_f32_e32 v109, v109
	s_nop 0
	v_mul_f32_e32 v109, v114, v109
	v_mul_f32_e32 v109, v109, v110
	v_mul_f32_e32 v110, 0xbfb8aa3b, v115
	v_exp_f32_e32 v110, v110
	s_nop 0
	v_add_f32_e32 v110, 1.0, v110
	v_rcp_f32_e32 v110, v110
	s_nop 0
	v_mul_f32_e32 v110, v115, v110
	v_mul_f32_e32 v110, v110, v111
	v_cvt_pk_bf16_f32 v109, v109, v110
	v_mul_f32_e32 v110, 0xbfb8aa3b, v104
	v_exp_f32_e32 v110, v110
	s_nop 0
	v_add_f32_e32 v110, 1.0, v110
	v_rcp_f32_e32 v110, v110
	s_nop 0
	v_mul_f32_e32 v104, v104, v110
	v_mul_f32_e32 v100, v104, v100
	v_mul_f32_e32 v104, 0xbfb8aa3b, v105
	v_exp_f32_e32 v104, v104
	s_nop 0
	v_add_f32_e32 v104, 1.0, v104
	v_rcp_f32_e32 v104, v104
	s_nop 0
	v_mul_f32_e32 v104, v105, v104
	v_mul_f32_e32 v101, v104, v101
	v_cvt_pk_bf16_f32 v110, v100, v101
	v_mul_f32_e32 v100, 0xbfb8aa3b, v106
	v_exp_f32_e32 v100, v100
	v_mul_f32_e32 v101, 0xbfb8aa3b, v107
	v_exp_f32_e32 v101, v101
	v_add_f32_e32 v100, 1.0, v100
	v_rcp_f32_e32 v100, v100
	v_add_f32_e32 v101, 1.0, v101
	v_rcp_f32_e32 v101, v101
	v_mul_f32_e32 v100, v106, v100
	v_mul_f32_e32 v100, v100, v102
	v_mul_f32_e32 v102, 0xbfb8aa3b, v96
	v_exp_f32_e32 v102, v102
	v_mul_f32_e32 v101, v107, v101
	v_mul_f32_e32 v101, v101, v103
	v_cvt_pk_bf16_f32 v111, v100, v101
	v_add_f32_e32 v102, 1.0, v102
	v_rcp_f32_e32 v102, v102
	v_or_b32_e32 v100, 32, v162
	v_mad_i64_i32 v[100:101], s[16:17], v100, s9, v[156:157]
	v_mul_f32_e32 v96, v96, v102
	v_mul_f32_e32 v92, v96, v92
	v_mul_f32_e32 v96, 0xbfb8aa3b, v97
	v_exp_f32_e32 v96, v96
	v_lshl_add_u64 v[100:101], v[100:101], 0, v[158:159]
	global_store_dwordx4 v[116:117], v[108:111], off
	v_add_f32_e32 v96, 1.0, v96
	v_rcp_f32_e32 v96, v96
	s_nop 0
	v_mul_f32_e32 v96, v97, v96
	v_mul_f32_e32 v93, v96, v93
	v_cvt_pk_bf16_f32 v92, v92, v93
	v_mul_f32_e32 v93, 0xbfb8aa3b, v98
	v_exp_f32_e32 v93, v93
	s_nop 0
	v_add_f32_e32 v93, 1.0, v93
	v_rcp_f32_e32 v93, v93
	s_nop 0
	v_mul_f32_e32 v93, v98, v93
	v_mul_f32_e32 v93, v93, v94
	v_mul_f32_e32 v94, 0xbfb8aa3b, v99
	v_exp_f32_e32 v94, v94
	s_nop 0
	v_add_f32_e32 v94, 1.0, v94
	v_rcp_f32_e32 v94, v94
	s_nop 0
	v_mul_f32_e32 v94, v99, v94
	v_mul_f32_e32 v94, v94, v95
	v_cvt_pk_bf16_f32 v93, v93, v94
	v_mul_f32_e32 v94, 0xbfb8aa3b, v88
	v_exp_f32_e32 v94, v94
	s_nop 0
	v_add_f32_e32 v94, 1.0, v94
	v_rcp_f32_e32 v94, v94
	s_nop 0
	v_mul_f32_e32 v88, v88, v94
	v_mul_f32_e32 v84, v88, v84
	v_mul_f32_e32 v88, 0xbfb8aa3b, v89
	v_exp_f32_e32 v88, v88
	s_nop 0
	v_add_f32_e32 v88, 1.0, v88
	v_rcp_f32_e32 v88, v88
	s_nop 0
	v_mul_f32_e32 v88, v89, v88
	v_mul_f32_e32 v85, v88, v85
	v_cvt_pk_bf16_f32 v94, v84, v85
	v_mul_f32_e32 v84, 0xbfb8aa3b, v90
	v_exp_f32_e32 v84, v84
	v_mul_f32_e32 v85, 0xbfb8aa3b, v91
	v_exp_f32_e32 v85, v85
	v_add_f32_e32 v84, 1.0, v84
	v_rcp_f32_e32 v84, v84
	v_add_f32_e32 v85, 1.0, v85
	v_rcp_f32_e32 v85, v85
	v_mul_f32_e32 v84, v90, v84
	v_mul_f32_e32 v84, v84, v86
	v_mul_f32_e32 v86, 0xbfb8aa3b, v80
	v_exp_f32_e32 v86, v86
	v_mul_f32_e32 v85, v91, v85
	v_mul_f32_e32 v85, v85, v87
	v_cvt_pk_bf16_f32 v95, v84, v85
	v_add_f32_e32 v86, 1.0, v86
	v_rcp_f32_e32 v86, v86
	v_or_b32_e32 v84, 48, v162
	v_mad_i64_i32 v[84:85], s[16:17], v84, s9, v[156:157]
	v_mul_f32_e32 v80, v80, v86
	v_mul_f32_e32 v76, v80, v76
	v_mul_f32_e32 v80, 0xbfb8aa3b, v81
	v_exp_f32_e32 v80, v80
	v_lshl_add_u64 v[84:85], v[84:85], 0, v[158:159]
	global_store_dwordx4 v[100:101], v[92:95], off
	v_add_f32_e32 v80, 1.0, v80
	v_rcp_f32_e32 v80, v80
	s_nop 0
	v_mul_f32_e32 v80, v81, v80
	v_mul_f32_e32 v77, v80, v77
	v_cvt_pk_bf16_f32 v76, v76, v77
	v_mul_f32_e32 v77, 0xbfb8aa3b, v82
	v_exp_f32_e32 v77, v77
	s_nop 0
	v_add_f32_e32 v77, 1.0, v77
	v_rcp_f32_e32 v77, v77
	s_nop 0
	v_mul_f32_e32 v77, v82, v77
	v_mul_f32_e32 v77, v77, v78
	v_mul_f32_e32 v78, 0xbfb8aa3b, v83
	v_exp_f32_e32 v78, v78
	s_nop 0
	v_add_f32_e32 v78, 1.0, v78
	v_rcp_f32_e32 v78, v78
	s_nop 0
	v_mul_f32_e32 v78, v83, v78
	v_mul_f32_e32 v78, v78, v79
	v_cvt_pk_bf16_f32 v77, v77, v78
	v_mul_f32_e32 v78, 0xbfb8aa3b, v72
	v_exp_f32_e32 v78, v78
	s_nop 0
	v_add_f32_e32 v78, 1.0, v78
	v_rcp_f32_e32 v78, v78
	s_nop 0
	v_mul_f32_e32 v72, v72, v78
	v_mul_f32_e32 v68, v72, v68
	v_mul_f32_e32 v72, 0xbfb8aa3b, v73
	v_exp_f32_e32 v72, v72
	s_nop 0
	v_add_f32_e32 v72, 1.0, v72
	v_rcp_f32_e32 v72, v72
	s_nop 0
	v_mul_f32_e32 v72, v73, v72
	v_mul_f32_e32 v69, v72, v69
	v_cvt_pk_bf16_f32 v78, v68, v69
	v_mul_f32_e32 v68, 0xbfb8aa3b, v74
	v_exp_f32_e32 v68, v68
	v_mul_f32_e32 v69, 0xbfb8aa3b, v75
	v_exp_f32_e32 v69, v69
	v_add_f32_e32 v68, 1.0, v68
	v_rcp_f32_e32 v68, v68
	v_add_f32_e32 v69, 1.0, v69
	v_rcp_f32_e32 v69, v69
	v_mul_f32_e32 v68, v74, v68
	v_mul_f32_e32 v68, v68, v70
	v_mul_f32_e32 v70, 0xbfb8aa3b, v64
	v_exp_f32_e32 v70, v70
	v_mul_f32_e32 v69, v75, v69
	v_mul_f32_e32 v69, v69, v71
	v_cvt_pk_bf16_f32 v79, v68, v69
; __device__ __forceinline__ unsigned pk2(float lo, float hi) { unsigned r; asm("v_cvt_pk_bf16_f32 %0, %1, %2" : "=v"(r) : "v"(lo), "v"(hi)); return r; }
; __device__ __forceinline__ float silu(float x) { return x * sigm(x); }
;     __device__ __forceinline__ void operator()(const f32x4 (&acc)[2][2][4][2], const Unit& u, int wr, int wc, int fr, int fq) const {
;     ...
;             for (int m = 0; m < 4; ++m) { bf16_t* rowp = O + (size_t)(row0 + ai * HALF + m * 16) * ldc + col0;
;                 const f32x4 g0 = acc[ai][0][m][0], g1 = acc[ai][0][m][1], u0 = acc[ai][1][m][0], u1 = acc[ai][1][m][1];
;                 u32x4 w; w.x = pk2(silu(g0[0]) * u0[0], silu(g0[1]) * u0[1]); w.y = pk2(silu(g0[2]) * u0[2], silu(g0[3]) * u0[3]);
;                 w.z = pk2(silu(g1[0]) * u1[0], silu(g1[1]) * u1[1]); w.w = pk2(silu(g1[2]) * u1[2], silu(g1[3]) * u1[3]);
;                 *(u32x4*)rowp = w; }
	v_add_f32_e32 v70, 1.0, v70
	v_rcp_f32_e32 v70, v70
	v_add_u32_e32 v68, 0x80, v162
	v_mad_i64_i32 v[68:69], s[16:17], v68, s9, v[156:157]
	v_mul_f32_e32 v64, v64, v70
	v_mul_f32_e32 v60, v64, v60
	v_mul_f32_e32 v64, 0xbfb8aa3b, v65
	v_exp_f32_e32 v64, v64
	v_lshl_add_u64 v[68:69], v[68:69], 0, v[158:159]
	global_store_dwordx4 v[84:85], v[76:79], off
	v_add_f32_e32 v64, 1.0, v64
	v_rcp_f32_e32 v64, v64
	s_nop 0
	v_mul_f32_e32 v64, v65, v64
	v_mul_f32_e32 v61, v64, v61
	v_cvt_pk_bf16_f32 v60, v60, v61
	v_mul_f32_e32 v61, 0xbfb8aa3b, v66
	v_exp_f32_e32 v61, v61
	s_nop 0
	v_add_f32_e32 v61, 1.0, v61
	v_rcp_f32_e32 v61, v61
	s_nop 0
	v_mul_f32_e32 v61, v66, v61
	v_mul_f32_e32 v61, v61, v62
	v_mul_f32_e32 v62, 0xbfb8aa3b, v67
	v_exp_f32_e32 v62, v62
	s_nop 0
	v_add_f32_e32 v62, 1.0, v62
	v_rcp_f32_e32 v62, v62
	s_nop 0
	v_mul_f32_e32 v62, v67, v62
	v_mul_f32_e32 v62, v62, v63
	v_cvt_pk_bf16_f32 v61, v61, v62
	v_mul_f32_e32 v62, 0xbfb8aa3b, v56
	v_exp_f32_e32 v62, v62
	s_nop 0
	v_add_f32_e32 v62, 1.0, v62
	v_rcp_f32_e32 v62, v62
	s_nop 0
	v_mul_f32_e32 v56, v56, v62
	v_mul_f32_e32 v52, v56, v52
	v_mul_f32_e32 v56, 0xbfb8aa3b, v57
	v_exp_f32_e32 v56, v56
	s_nop 0
	v_add_f32_e32 v56, 1.0, v56
	v_rcp_f32_e32 v56, v56
	s_nop 0
	v_mul_f32_e32 v56, v57, v56
	v_mul_f32_e32 v53, v56, v53
	v_cvt_pk_bf16_f32 v62, v52, v53
	v_mul_f32_e32 v52, 0xbfb8aa3b, v58
	v_exp_f32_e32 v52, v52
	v_mul_f32_e32 v53, 0xbfb8aa3b, v59
	v_exp_f32_e32 v53, v53
	v_add_f32_e32 v52, 1.0, v52
	v_rcp_f32_e32 v52, v52
	v_add_f32_e32 v53, 1.0, v53
	v_rcp_f32_e32 v53, v53
	v_mul_f32_e32 v52, v58, v52
	v_mul_f32_e32 v52, v52, v54
	v_mul_f32_e32 v54, 0xbfb8aa3b, v48
	v_exp_f32_e32 v54, v54
	v_mul_f32_e32 v53, v59, v53
	v_mul_f32_e32 v53, v53, v55
	v_cvt_pk_bf16_f32 v63, v52, v53
	v_add_f32_e32 v54, 1.0, v54
	v_rcp_f32_e32 v54, v54
	v_add_u32_e32 v52, 0x90, v162
	v_mad_i64_i32 v[52:53], s[16:17], v52, s9, v[156:157]
	v_mul_f32_e32 v48, v48, v54
	v_mul_f32_e32 v44, v48, v44
	v_mul_f32_e32 v48, 0xbfb8aa3b, v49
	v_exp_f32_e32 v48, v48
	v_lshl_add_u64 v[52:53], v[52:53], 0, v[158:159]
	global_store_dwordx4 v[68:69], v[60:63], off
	v_add_f32_e32 v48, 1.0, v48
	v_rcp_f32_e32 v48, v48
	s_nop 0
	v_mul_f32_e32 v48, v49, v48
	v_mul_f32_e32 v45, v48, v45
	v_cvt_pk_bf16_f32 v44, v44, v45
	v_mul_f32_e32 v45, 0xbfb8aa3b, v50
	v_exp_f32_e32 v45, v45
	s_nop 0
	v_add_f32_e32 v45, 1.0, v45
	v_rcp_f32_e32 v45, v45
	s_nop 0
	v_mul_f32_e32 v45, v50, v45
	v_mul_f32_e32 v45, v45, v46
	v_mul_f32_e32 v46, 0xbfb8aa3b, v51
	v_exp_f32_e32 v46, v46
	s_nop 0
	v_add_f32_e32 v46, 1.0, v46
	v_rcp_f32_e32 v46, v46
	s_nop 0
	v_mul_f32_e32 v46, v51, v46
	v_mul_f32_e32 v46, v46, v47
	v_cvt_pk_bf16_f32 v45, v45, v46
	v_mul_f32_e32 v46, 0xbfb8aa3b, v40
	v_exp_f32_e32 v46, v46
	s_nop 0
	v_add_f32_e32 v46, 1.0, v46
	v_rcp_f32_e32 v46, v46
	s_nop 0
	v_mul_f32_e32 v40, v40, v46
	v_mul_f32_e32 v36, v40, v36
	v_mul_f32_e32 v40, 0xbfb8aa3b, v41
	v_exp_f32_e32 v40, v40
	s_nop 0
	v_add_f32_e32 v40, 1.0, v40
	v_rcp_f32_e32 v40, v40
	s_nop 0
	v_mul_f32_e32 v40, v41, v40
	v_mul_f32_e32 v37, v40, v37
	v_cvt_pk_bf16_f32 v46, v36, v37
	v_mul_f32_e32 v36, 0xbfb8aa3b, v42
	v_exp_f32_e32 v36, v36
	v_mul_f32_e32 v37, 0xbfb8aa3b, v43
	v_exp_f32_e32 v37, v37
	v_add_f32_e32 v36, 1.0, v36
	v_rcp_f32_e32 v36, v36
	v_add_f32_e32 v37, 1.0, v37
	v_rcp_f32_e32 v37, v37
	v_mul_f32_e32 v36, v42, v36
	v_mul_f32_e32 v36, v36, v38
	v_mul_f32_e32 v38, 0xbfb8aa3b, v32
	v_exp_f32_e32 v38, v38
	v_mul_f32_e32 v37, v43, v37
	v_mul_f32_e32 v37, v37, v39
	v_cvt_pk_bf16_f32 v47, v36, v37
	v_add_f32_e32 v38, 1.0, v38
	v_rcp_f32_e32 v38, v38
	v_add_u32_e32 v36, 0xa0, v162
	v_mad_i64_i32 v[36:37], s[16:17], v36, s9, v[156:157]
	v_mul_f32_e32 v32, v32, v38
	v_mul_f32_e32 v28, v32, v28
	v_mul_f32_e32 v32, 0xbfb8aa3b, v33
	v_exp_f32_e32 v32, v32
	v_lshl_add_u64 v[36:37], v[36:37], 0, v[158:159]
	global_store_dwordx4 v[52:53], v[44:47], off
	v_add_f32_e32 v32, 1.0, v32
	v_rcp_f32_e32 v32, v32
	s_nop 0
	v_mul_f32_e32 v32, v33, v32
	v_mul_f32_e32 v29, v32, v29
	v_cvt_pk_bf16_f32 v28, v28, v29
	v_mul_f32_e32 v29, 0xbfb8aa3b, v34
	v_exp_f32_e32 v29, v29
	s_nop 0
	v_add_f32_e32 v29, 1.0, v29
	v_rcp_f32_e32 v29, v29
	s_nop 0
	v_mul_f32_e32 v29, v34, v29
	v_mul_f32_e32 v29, v29, v30
	v_mul_f32_e32 v30, 0xbfb8aa3b, v35
	v_exp_f32_e32 v30, v30
	s_nop 0
	v_add_f32_e32 v30, 1.0, v30
	v_rcp_f32_e32 v30, v30
	s_nop 0
	v_mul_f32_e32 v30, v35, v30
	v_mul_f32_e32 v30, v30, v31
	v_cvt_pk_bf16_f32 v29, v29, v30
	v_mul_f32_e32 v30, 0xbfb8aa3b, v24
	v_exp_f32_e32 v30, v30
	s_nop 0
	v_add_f32_e32 v30, 1.0, v30
	v_rcp_f32_e32 v30, v30
	s_nop 0
	v_mul_f32_e32 v24, v24, v30
	v_mul_f32_e32 v20, v24, v20
	v_mul_f32_e32 v24, 0xbfb8aa3b, v25
	v_exp_f32_e32 v24, v24
	s_nop 0
	v_add_f32_e32 v24, 1.0, v24
	v_rcp_f32_e32 v24, v24
	s_nop 0
	v_mul_f32_e32 v24, v25, v24
	v_mul_f32_e32 v21, v24, v21
	v_cvt_pk_bf16_f32 v30, v20, v21
	v_mul_f32_e32 v20, 0xbfb8aa3b, v26
	v_exp_f32_e32 v20, v20
	v_mul_f32_e32 v21, 0xbfb8aa3b, v27
	v_exp_f32_e32 v21, v21
	v_add_f32_e32 v20, 1.0, v20
	v_rcp_f32_e32 v20, v20
	v_add_f32_e32 v21, 1.0, v21
	v_rcp_f32_e32 v21, v21
	v_mul_f32_e32 v20, v26, v20
	v_mul_f32_e32 v20, v20, v22
	v_mul_f32_e32 v22, 0xbfb8aa3b, v16
	v_exp_f32_e32 v22, v22
	v_mul_f32_e32 v21, v27, v21
	v_mul_f32_e32 v21, v21, v23
	v_cvt_pk_bf16_f32 v31, v20, v21
	v_add_f32_e32 v22, 1.0, v22
	v_rcp_f32_e32 v22, v22
	v_add_u32_e32 v20, 0xb0, v162
	v_mad_i64_i32 v[20:21], s[16:17], v20, s9, v[156:157]
	v_mul_f32_e32 v16, v16, v22
	v_mul_f32_e32 v12, v16, v12
	v_mul_f32_e32 v16, 0xbfb8aa3b, v17
	v_exp_f32_e32 v16, v16
	v_lshl_add_u64 v[20:21], v[20:21], 0, v[158:159]
	s_mov_b32 s16, s8
	global_store_dwordx4 v[36:37], v[28:31], off
	v_add_f32_e32 v16, 1.0, v16
	v_rcp_f32_e32 v16, v16
	s_nop 0
	v_mul_f32_e32 v16, v17, v16
	v_mul_f32_e32 v13, v16, v13
	v_cvt_pk_bf16_f32 v12, v12, v13
	v_mul_f32_e32 v13, 0xbfb8aa3b, v18
	v_exp_f32_e32 v13, v13
	s_nop 0
	v_add_f32_e32 v13, 1.0, v13
	v_rcp_f32_e32 v13, v13
	s_nop 0
	v_mul_f32_e32 v13, v18, v13
	v_mul_f32_e32 v13, v13, v14
	v_mul_f32_e32 v14, 0xbfb8aa3b, v19
	v_exp_f32_e32 v14, v14
	s_nop 0
	v_add_f32_e32 v14, 1.0, v14
	v_rcp_f32_e32 v14, v14
	s_nop 0
	v_mul_f32_e32 v14, v19, v14
	v_mul_f32_e32 v14, v14, v15
	v_cvt_pk_bf16_f32 v13, v13, v14
	v_mul_f32_e32 v14, 0xbfb8aa3b, v8
	v_exp_f32_e32 v14, v14
	s_nop 0
	v_add_f32_e32 v14, 1.0, v14
	v_rcp_f32_e32 v14, v14
	s_nop 0
	v_mul_f32_e32 v8, v8, v14
	v_mul_f32_e32 v4, v8, v4
	v_mul_f32_e32 v8, 0xbfb8aa3b, v9
	v_exp_f32_e32 v8, v8
	s_nop 0
	v_add_f32_e32 v8, 1.0, v8
	v_rcp_f32_e32 v8, v8
	s_nop 0
	v_mul_f32_e32 v8, v9, v8
	v_mul_f32_e32 v5, v8, v5
	v_cvt_pk_bf16_f32 v14, v4, v5
	v_mul_f32_e32 v4, 0xbfb8aa3b, v10
	v_mul_f32_e32 v5, 0xbfb8aa3b, v11
	v_exp_f32_e32 v4, v4
	v_exp_f32_e32 v5, v5
	v_add_f32_e32 v4, 1.0, v4
	v_add_f32_e32 v5, 1.0, v5
	v_rcp_f32_e32 v4, v4
	v_rcp_f32_e32 v5, v5
	v_mul_f32_e32 v4, v10, v4
	v_mul_f32_e32 v5, v11, v5
	v_mul_f32_e32 v4, v4, v6
	v_mul_f32_e32 v5, v5, v7
	v_cvt_pk_bf16_f32 v15, v4, v5
	global_store_dwordx4 v[20:21], v[12:15], off
	s_cbranch_vccz .LBB0_79
; #define PG8_WAIT_V(n) asm volatile("s_waitcnt vmcnt(" #n ")" ::: "memory")
; #define PG8_BAR __builtin_amdgcn_s_barrier()
; template <class Epi>
; __device__ __forceinline__ void gemm_phase(LAS unsigned char* lds, const Gemm g, const int G, const int cidx, const Epi& E) {
;     ...
;     PG8_WAIT_V(0);
;     if (wr == 0) PG8_BAR;
;     PG8_BAR;
	s_waitcnt vmcnt(0)
	s_cmpk_gt_u32 s95, 0xff
	s_mov_b32 s73, s83
	v_readlane_b32 s79, v255, 21
	s_cbranch_scc1 .LBB0_86
	s_barrier

; #define PG8_STAGE(bufoff, gbase, voff) do { _Pragma("unroll") for (int _i = 0; _i < 2; ++_i) \
;         __builtin_amdgcn_global_load_lds((const unsigned*)((const char*)(gbase) + (voff)[_i]), (LAS unsigned*)(lds + (bufoff) + ldsw + _i * 8192), 16, 0, 0); } while (0)
; #define PG8_LDA(dst, b, h) do { _Pragma("unroll") for (int m = 0; m < 4; ++m) _Pragma("unroll") for (int k = 0; k < 2; ++k) dst[m][k] = *(const LAS bf16x8*)(lds + PG8_SA(b, h) + aoff + m * 2048 + k * 1024); } while (0)
; #define PG8_LDB(dst, b, h) do { _Pragma("unroll") for (int n = 0; n < 2; ++n) _Pragma("unroll") for (int k = 0; k < 2; ++k) dst[n][k] = *(const LAS bf16x8*)(lds + PG8_SB(b, h) + boff + n * 2048 + k * 1024); } while (0)
; #define PG8_MMA(ai, bj, At, Bt) do { __builtin_amdgcn_s_setprio(1); _Pragma("unroll") for (int m = 0; m < 4; ++m) _Pragma("unroll") for (int n = 0; n < 2; ++n) _Pragma("unroll") for (int k = 0; k < 2; ++k) \
;         acc[ai][bj][m][n] = __builtin_amdgcn_mfma_f32_16x16x32_bf16(Bt[n][k], At[m][k], acc[ai][bj][m][n], 0, 0, 0); __builtin_amdgcn_s_setprio(0); } while (0)
; #define PG8_WAIT_V(n) asm volatile("s_waitcnt vmcnt(" #n ")" ::: "memory")
; #define PG8_WAIT_L(n) asm volatile("s_waitcnt lgkmcnt(" #n ")" ::: "memory")
; #define PG8_BAR __builtin_amdgcn_s_barrier()
; #define PG8_SCHED __builtin_amdgcn_sched_barrier(0)
; template <class Epi>
; __device__ __forceinline__ void gemm_phase(LAS unsigned char* lds, const Gemm g, const int G, const int cidx, const Epi& E) {
;     ...
;             const char* a1 = cA + (size_t)(t + 1) * kstep;
;             const char* a2 = last ? nA : cA + (size_t)(t + 2) * kstep; const char* b2 = last ? nB : cB + (size_t)(t + 2) * kstep;
;             const char* a3 = a2 + kstep; const char* b3 = b2 + kstep;
;             PG8_LDB(B0, 0, 0); PG8_LDB(B1, 0, 1); PG8_SCHED; PG8_LDA(At, 0, 0); PG8_STAGE(PG8_SA(1, 1), a1 + hstep, voffA);
;             PG8_WAIT_V(8); PG8_WAIT_L(0); PG8_BAR; PG8_MMA(0, 0, At, B0); PG8_MMA(0, 1, At, B1); PG8_BAR; PG8_SCHED;
;             PG8_LDA(At, 0, 1); PG8_STAGE(PG8_SB(0, 0), b2, voffB); PG8_STAGE(PG8_SB(0, 1), b2 + hstep, voffB); PG8_STAGE(PG8_SA(0, 0), a2, voffA);
.LBB0_216:
	s_add_u32 s72, s8, s70
	s_addc_u32 s73, s9, s71
	s_add_u32 s72, s72, 0x100
	s_addc_u32 s73, s73, 0
	s_add_u32 s83, s43, s70
	s_addc_u32 s86, s44, s71
	s_add_i32 s87, 0, 0x10000
	s_cmpk_eq_i32 s70, 0x700
	s_cselect_b32 s75, s31, s73
	s_cselect_b32 s74, s45, s72
	v_add_u32_e32 v3, s87, v158
	s_cselect_b32 s73, s29, s86
	s_cselect_b32 s72, s68, s83
	s_add_i32 s83, 0, 0x14000
	ds_read_b128 v[132:135], v3
	ds_read_b128 v[140:143], v3 offset:1024
	ds_read_b128 v[160:163], v3 offset:2048
	ds_read_b128 v[164:167], v3 offset:3072
	v_add_u32_e32 v3, s83, v158
	ds_read_b128 v[168:171], v3
	ds_read_b128 v[172:175], v3 offset:1024
	ds_read_b128 v[176:179], v3 offset:2048
	ds_read_b128 v[180:183], v3 offset:3072
	v_lshl_add_u64 v[200:201], v[154:155], 0, s[70:71]
	s_add_i32 m0, s19, 0xc000
	ds_read_b128 v[184:187], v159
	ds_read_b128 v[188:191], v159 offset:1024
	ds_read_b128 v[192:195], v159 offset:2048
	ds_read_b128 v[196:199], v159 offset:3072
	ds_read_b128 v[214:217], v159 offset:4096
	ds_read_b128 v[218:221], v159 offset:5120
	ds_read_b128 v[222:225], v159 offset:6144
	ds_read_b128 v[226:229], v159 offset:7168
	global_load_lds_dwordx4 v[200:201], off
	v_lshl_add_u64 v[200:201], v[0:1], 0, s[70:71]
	s_add_i32 m0, s19, 0xe000
	s_nop 0
	global_load_lds_dwordx4 v[200:201], off
	s_waitcnt vmcnt(8)
	s_waitcnt lgkmcnt(0)
	s_barrier
	s_setprio 1
	v_mfma_f32_16x16x32_bf16 v[64:67], v[132:135], v[184:187], v[64:67]
	v_mfma_f32_16x16x32_bf16 v[72:75], v[160:163], v[184:187], v[72:75]
	v_mfma_f32_16x16x32_bf16 v[92:95], v[132:135], v[192:195], v[92:95]
	v_mfma_f32_16x16x32_bf16 v[96:99], v[160:163], v[192:195], v[96:99]
	v_mfma_f32_16x16x32_bf16 v[116:119], v[132:135], v[214:217], v[116:119]
	v_mfma_f32_16x16x32_bf16 v[124:127], v[160:163], v[214:217], v[124:127]
	v_mfma_f32_16x16x32_bf16 v[112:115], v[132:135], v[222:225], v[112:115]
	v_mfma_f32_16x16x32_bf16 v[100:103], v[160:163], v[222:225], v[100:103]
	v_mfma_f32_16x16x32_bf16 v[64:67], v[140:143], v[188:191], v[64:67]
	v_mfma_f32_16x16x32_bf16 v[72:75], v[164:167], v[188:191], v[72:75]
	v_mfma_f32_16x16x32_bf16 v[92:95], v[140:143], v[196:199], v[92:95]
	v_mfma_f32_16x16x32_bf16 v[96:99], v[164:167], v[196:199], v[96:99]
	v_mfma_f32_16x16x32_bf16 v[116:119], v[140:143], v[218:221], v[116:119]
	v_mfma_f32_16x16x32_bf16 v[124:127], v[164:167], v[218:221], v[124:127]
	v_mfma_f32_16x16x32_bf16 v[112:115], v[140:143], v[226:229], v[112:115]
	v_mfma_f32_16x16x32_bf16 v[100:103], v[164:167], v[226:229], v[100:103]
	v_mfma_f32_16x16x32_bf16 v[76:79], v[168:171], v[184:187], v[76:79]
	v_mfma_f32_16x16x32_bf16 v[84:87], v[176:179], v[184:187], v[84:87]
	v_mfma_f32_16x16x32_bf16 v[104:107], v[168:171], v[192:195], v[104:107]
	v_mfma_f32_16x16x32_bf16 v[108:111], v[176:179], v[192:195], v[108:111]
	v_mfma_f32_16x16x32_bf16 v[128:131], v[168:171], v[214:217], v[128:131]
	v_mfma_f32_16x16x32_bf16 v[120:123], v[176:179], v[214:217], v[120:123]
	v_mfma_f32_16x16x32_bf16 v[88:91], v[168:171], v[222:225], v[88:91]
	v_mfma_f32_16x16x32_bf16 v[80:83], v[176:179], v[222:225], v[80:83]
	v_mfma_f32_16x16x32_bf16 v[76:79], v[172:175], v[188:191], v[76:79]
	v_mfma_f32_16x16x32_bf16 v[84:87], v[180:183], v[188:191], v[84:87]
	v_mfma_f32_16x16x32_bf16 v[104:107], v[172:175], v[196:199], v[104:107]
	v_mfma_f32_16x16x32_bf16 v[108:111], v[180:183], v[196:199], v[108:111]
	v_mfma_f32_16x16x32_bf16 v[128:131], v[172:175], v[218:221], v[128:131]
	v_mfma_f32_16x16x32_bf16 v[120:123], v[180:183], v[218:221], v[120:123]
	v_mfma_f32_16x16x32_bf16 v[88:91], v[172:175], v[226:229], v[88:91]
	v_mfma_f32_16x16x32_bf16 v[80:83], v[180:183], v[226:229], v[80:83]
	s_setprio 0
	s_barrier
	s_add_i32 s86, s87, s40
	v_lshl_add_u64 v[200:201], s[72:73], 0, v[146:147]
	s_mov_b32 m0, s86
	ds_read_b128 v[184:187], v159 offset:16384
	ds_read_b128 v[188:191], v159 offset:17408
	ds_read_b128 v[192:195], v159 offset:18432
	ds_read_b128 v[196:199], v159 offset:19456
	ds_read_b128 v[214:217], v159 offset:20480
	ds_read_b128 v[218:221], v159 offset:21504
	ds_read_b128 v[222:225], v159 offset:22528
	ds_read_b128 v[226:229], v159 offset:23552
	global_load_lds_dwordx4 v[200:201], off
	s_add_i32 m0, s86, 0x2000
	s_add_u32 s86, s72, 0x40000
	v_lshl_add_u64 v[230:231], s[72:73], 0, v[148:149]
	s_addc_u32 s87, s73, 0
	s_add_i32 s83, s83, s40
	global_load_lds_dwordx4 v[230:231], off
	v_lshl_add_u64 v[232:233], s[86:87], 0, v[146:147]
	s_mov_b32 m0, s83
	v_lshl_add_u64 v[234:235], s[74:75], 0, v[148:149]
	global_load_lds_dwordx4 v[232:233], off
	v_lshl_add_u64 v[232:233], s[86:87], 0, v[148:149]
	s_add_i32 m0, s83, 0x2000
	s_nop 0
	global_load_lds_dwordx4 v[232:233], off
	v_lshl_add_u64 v[232:233], s[74:75], 0, v[146:147]
	s_mov_b32 m0, s19
	s_nop 0
	global_load_lds_dwordx4 v[232:233], off
	s_mov_b32 m0, s76
	s_nop 0
	global_load_lds_dwordx4 v[234:235], off
	s_waitcnt vmcnt(8)
	s_waitcnt lgkmcnt(0)
	s_barrier
; #define PG8_STAGE(bufoff, gbase, voff) do { _Pragma("unroll") for (int _i = 0; _i < 2; ++_i) \
;         __builtin_amdgcn_global_load_lds((const unsigned*)((const char*)(gbase) + (voff)[_i]), (LAS unsigned*)(lds + (bufoff) + ldsw + _i * 8192), 16, 0, 0); } while (0)
; #define PG8_LDA(dst, b, h) do { _Pragma("unroll") for (int m = 0; m < 4; ++m) _Pragma("unroll") for (int k = 0; k < 2; ++k) dst[m][k] = *(const LAS bf16x8*)(lds + PG8_SA(b, h) + aoff + m * 2048 + k * 1024); } while (0)
; #define PG8_LDB(dst, b, h) do { _Pragma("unroll") for (int n = 0; n < 2; ++n) _Pragma("unroll") for (int k = 0; k < 2; ++k) dst[n][k] = *(const LAS bf16x8*)(lds + PG8_SB(b, h) + boff + n * 2048 + k * 1024); } while (0)
; #define PG8_MMA(ai, bj, At, Bt) do { __builtin_amdgcn_s_setprio(1); _Pragma("unroll") for (int m = 0; m < 4; ++m) _Pragma("unroll") for (int n = 0; n < 2; ++n) _Pragma("unroll") for (int k = 0; k < 2; ++k) \
;         acc[ai][bj][m][n] = __builtin_amdgcn_mfma_f32_16x16x32_bf16(Bt[n][k], At[m][k], acc[ai][bj][m][n], 0, 0, 0); __builtin_amdgcn_s_setprio(0); } while (0)
; #define PG8_WAIT_V(n) asm volatile("s_waitcnt vmcnt(" #n ")" ::: "memory")
; #define PG8_WAIT_L(n) asm volatile("s_waitcnt lgkmcnt(" #n ")" ::: "memory")
; #define PG8_BAR __builtin_amdgcn_s_barrier()
; #define PG8_SCHED __builtin_amdgcn_sched_barrier(0)
; template <class Epi>
; __device__ __forceinline__ void gemm_phase(LAS unsigned char* lds, const Gemm g, const int G, const int cidx, const Epi& E) {
;     ...
;             PG8_WAIT_V(8); PG8_WAIT_L(0); PG8_BAR; PG8_MMA(1, 0, At, B0); PG8_MMA(1, 1, At, B1); PG8_BAR; PG8_SCHED;
;             PG8_LDB(B0, 1, 0); PG8_LDB(B1, 1, 1); PG8_SCHED; PG8_LDA(At, 1, 0); PG8_STAGE(PG8_SA(0, 1), a2 + hstep, voffA);
;             PG8_WAIT_V(8); PG8_WAIT_L(0); PG8_BAR; PG8_MMA(0, 0, At, B0); PG8_MMA(0, 1, At, B1); PG8_BAR; PG8_SCHED;
	s_setprio 1
	v_mfma_f32_16x16x32_bf16 v[68:71], v[132:135], v[184:187], v[68:71]
	v_mfma_f32_16x16x32_bf16 v[60:63], v[160:163], v[184:187], v[60:63]
	v_mfma_f32_16x16x32_bf16 v[48:51], v[132:135], v[192:195], v[48:51]
	v_mfma_f32_16x16x32_bf16 v[44:47], v[160:163], v[192:195], v[44:47]
	v_mfma_f32_16x16x32_bf16 v[32:35], v[132:135], v[214:217], v[32:35]
	v_mfma_f32_16x16x32_bf16 v[28:31], v[160:163], v[214:217], v[28:31]
	v_mfma_f32_16x16x32_bf16 v[16:19], v[132:135], v[222:225], v[16:19]
	v_mfma_f32_16x16x32_bf16 v[12:15], v[160:163], v[222:225], v[12:15]
	v_mfma_f32_16x16x32_bf16 v[68:71], v[140:143], v[188:191], v[68:71]
	v_mfma_f32_16x16x32_bf16 v[60:63], v[164:167], v[188:191], v[60:63]
	v_mfma_f32_16x16x32_bf16 v[48:51], v[140:143], v[196:199], v[48:51]
	v_mfma_f32_16x16x32_bf16 v[44:47], v[164:167], v[196:199], v[44:47]
	v_mfma_f32_16x16x32_bf16 v[32:35], v[140:143], v[218:221], v[32:35]
	v_mfma_f32_16x16x32_bf16 v[28:31], v[164:167], v[218:221], v[28:31]
	v_mfma_f32_16x16x32_bf16 v[16:19], v[140:143], v[226:229], v[16:19]
	v_mfma_f32_16x16x32_bf16 v[12:15], v[164:167], v[226:229], v[12:15]
	v_mfma_f32_16x16x32_bf16 v[56:59], v[168:171], v[184:187], v[56:59]
	v_mfma_f32_16x16x32_bf16 v[52:55], v[176:179], v[184:187], v[52:55]
	v_mfma_f32_16x16x32_bf16 v[40:43], v[168:171], v[192:195], v[40:43]
	v_mfma_f32_16x16x32_bf16 v[36:39], v[176:179], v[192:195], v[36:39]
	v_mfma_f32_16x16x32_bf16 v[24:27], v[168:171], v[214:217], v[24:27]
	v_mfma_f32_16x16x32_bf16 v[20:23], v[176:179], v[214:217], v[20:23]
	v_mfma_f32_16x16x32_bf16 v[8:11], v[168:171], v[222:225], v[8:11]
	v_mfma_f32_16x16x32_bf16 v[4:7], v[176:179], v[222:225], v[4:7]
	v_mfma_f32_16x16x32_bf16 v[56:59], v[172:175], v[188:191], v[56:59]
	v_mfma_f32_16x16x32_bf16 v[52:55], v[180:183], v[188:191], v[52:55]
	v_mfma_f32_16x16x32_bf16 v[40:43], v[172:175], v[196:199], v[40:43]
	v_mfma_f32_16x16x32_bf16 v[36:39], v[180:183], v[196:199], v[36:39]
	v_mfma_f32_16x16x32_bf16 v[24:27], v[172:175], v[218:221], v[24:27]
	v_mfma_f32_16x16x32_bf16 v[20:23], v[180:183], v[218:221], v[20:23]
	v_mfma_f32_16x16x32_bf16 v[8:11], v[172:175], v[226:229], v[8:11]
	v_mfma_f32_16x16x32_bf16 v[4:7], v[180:183], v[226:229], v[4:7]
	s_setprio 0
	s_barrier
	s_add_i32 s83, 0, 0x18000
	v_add_u32_e32 v3, s83, v158
	s_add_i32 s86, 0, 0x1c000
	ds_read_b128 v[132:135], v3
	ds_read_b128 v[140:143], v3 offset:1024
	ds_read_b128 v[160:163], v3 offset:2048
	ds_read_b128 v[164:167], v3 offset:3072
	v_add_u32_e32 v3, s86, v158
	ds_read_b128 v[168:171], v3
	ds_read_b128 v[172:175], v3 offset:1024
	ds_read_b128 v[176:179], v3 offset:2048
	ds_read_b128 v[180:183], v3 offset:3072
	s_add_u32 s74, s74, 0x40000
	s_addc_u32 s75, s75, 0
	s_mov_b32 m0, s84
	v_lshl_add_u64 v[236:237], s[74:75], 0, v[146:147]
	ds_read_b128 v[184:187], v159 offset:32768
	ds_read_b128 v[188:191], v159 offset:33792
	ds_read_b128 v[192:195], v159 offset:34816
	ds_read_b128 v[196:199], v159 offset:35840
	ds_read_b128 v[214:217], v159 offset:36864
	ds_read_b128 v[218:221], v159 offset:37888
	ds_read_b128 v[222:225], v159 offset:38912
	ds_read_b128 v[226:229], v159 offset:39936
	global_load_lds_dwordx4 v[236:237], off
	v_lshl_add_u64 v[236:237], s[74:75], 0, v[148:149]
	s_mov_b32 m0, s97
	s_nop 0
	global_load_lds_dwordx4 v[236:237], off
	s_waitcnt vmcnt(8)
	s_waitcnt lgkmcnt(0)
	s_barrier
	s_setprio 1
	v_mfma_f32_16x16x32_bf16 v[64:67], v[132:135], v[184:187], v[64:67]
	v_mfma_f32_16x16x32_bf16 v[72:75], v[160:163], v[184:187], v[72:75]
	v_mfma_f32_16x16x32_bf16 v[92:95], v[132:135], v[192:195], v[92:95]
	v_mfma_f32_16x16x32_bf16 v[96:99], v[160:163], v[192:195], v[96:99]
	v_mfma_f32_16x16x32_bf16 v[116:119], v[132:135], v[214:217], v[116:119]
	v_mfma_f32_16x16x32_bf16 v[124:127], v[160:163], v[214:217], v[124:127]
	v_mfma_f32_16x16x32_bf16 v[112:115], v[132:135], v[222:225], v[112:115]
	v_mfma_f32_16x16x32_bf16 v[100:103], v[160:163], v[222:225], v[100:103]
	v_mfma_f32_16x16x32_bf16 v[64:67], v[140:143], v[188:191], v[64:67]
	v_mfma_f32_16x16x32_bf16 v[72:75], v[164:167], v[188:191], v[72:75]
	v_mfma_f32_16x16x32_bf16 v[92:95], v[140:143], v[196:199], v[92:95]
	v_mfma_f32_16x16x32_bf16 v[96:99], v[164:167], v[196:199], v[96:99]
	v_mfma_f32_16x16x32_bf16 v[116:119], v[140:143], v[218:221], v[116:119]
	v_mfma_f32_16x16x32_bf16 v[124:127], v[164:167], v[218:221], v[124:127]
	v_mfma_f32_16x16x32_bf16 v[112:115], v[140:143], v[226:229], v[112:115]
	v_mfma_f32_16x16x32_bf16 v[100:103], v[164:167], v[226:229], v[100:103]
	v_mfma_f32_16x16x32_bf16 v[76:79], v[168:171], v[184:187], v[76:79]
	v_mfma_f32_16x16x32_bf16 v[84:87], v[176:179], v[184:187], v[84:87]
	v_mfma_f32_16x16x32_bf16 v[104:107], v[168:171], v[192:195], v[104:107]
	v_mfma_f32_16x16x32_bf16 v[108:111], v[176:179], v[192:195], v[108:111]
	v_mfma_f32_16x16x32_bf16 v[128:131], v[168:171], v[214:217], v[128:131]
	v_mfma_f32_16x16x32_bf16 v[120:123], v[176:179], v[214:217], v[120:123]
	v_mfma_f32_16x16x32_bf16 v[88:91], v[168:171], v[222:225], v[88:91]
	v_mfma_f32_16x16x32_bf16 v[80:83], v[176:179], v[222:225], v[80:83]
	v_mfma_f32_16x16x32_bf16 v[76:79], v[172:175], v[188:191], v[76:79]
	v_mfma_f32_16x16x32_bf16 v[84:87], v[180:183], v[188:191], v[84:87]
	v_mfma_f32_16x16x32_bf16 v[104:107], v[172:175], v[196:199], v[104:107]
	v_mfma_f32_16x16x32_bf16 v[108:111], v[180:183], v[196:199], v[108:111]
	v_mfma_f32_16x16x32_bf16 v[128:131], v[172:175], v[218:221], v[128:131]
	v_mfma_f32_16x16x32_bf16 v[120:123], v[180:183], v[218:221], v[120:123]
	v_mfma_f32_16x16x32_bf16 v[88:91], v[172:175], v[226:229], v[88:91]
	v_mfma_f32_16x16x32_bf16 v[80:83], v[180:183], v[226:229], v[80:83]
	s_setprio 0
	s_barrier
; #define PG8_STAGE(bufoff, gbase, voff) do { _Pragma("unroll") for (int _i = 0; _i < 2; ++_i) \
;         __builtin_amdgcn_global_load_lds((const unsigned*)((const char*)(gbase) + (voff)[_i]), (LAS unsigned*)(lds + (bufoff) + ldsw + _i * 8192), 16, 0, 0); } while (0)
; #define PG8_LDA(dst, b, h) do { _Pragma("unroll") for (int m = 0; m < 4; ++m) _Pragma("unroll") for (int k = 0; k < 2; ++k) dst[m][k] = *(const LAS bf16x8*)(lds + PG8_SA(b, h) + aoff + m * 2048 + k * 1024); } while (0)
; #define PG8_MMA(ai, bj, At, Bt) do { __builtin_amdgcn_s_setprio(1); _Pragma("unroll") for (int m = 0; m < 4; ++m) _Pragma("unroll") for (int n = 0; n < 2; ++n) _Pragma("unroll") for (int k = 0; k < 2; ++k) \
;         acc[ai][bj][m][n] = __builtin_amdgcn_mfma_f32_16x16x32_bf16(Bt[n][k], At[m][k], acc[ai][bj][m][n], 0, 0, 0); __builtin_amdgcn_s_setprio(0); } while (0)
; #define PG8_WAIT_V(n) asm volatile("s_waitcnt vmcnt(" #n ")" ::: "memory")
; #define PG8_WAIT_L(n) asm volatile("s_waitcnt lgkmcnt(" #n ")" ::: "memory")
; #define PG8_BAR __builtin_amdgcn_s_barrier()
; #define PG8_SCHED __builtin_amdgcn_sched_barrier(0)
; template <class Epi>
; __device__ __forceinline__ void gemm_phase(LAS unsigned char* lds, const Gemm g, const int G, const int cidx, const Epi& E) {
;     ...
;             PG8_LDA(At, 1, 1); PG8_STAGE(PG8_SB(1, 0), b3, voffB); PG8_STAGE(PG8_SB(1, 1), b3 + hstep, voffB); PG8_STAGE(PG8_SA(1, 0), a3, voffA);
;             PG8_WAIT_V(8); PG8_WAIT_L(0); PG8_BAR; PG8_MMA(1, 0, At, B0); PG8_MMA(1, 1, At, B1); PG8_BAR; PG8_SCHED;
;         }
;         if constexpr (!Epi::AFTER_DRAIN) E(acc, cur, wr, wc, fr, fq);
;         if (!has_next) break;
; #pragma unroll
;         for (int a = 0; a < 2; ++a)
; #pragma unroll
;             for (int b = 0; b < 2; ++b)
; #pragma unroll
;                 for (int m = 0; m < 4; ++m)
; #pragma unroll
;                     for (int n = 0; n < 2; ++n) acc[a][b][m][n] = ZERO4;
;         cur = nxt; cA = nA; cB = nB; ++ui;
	s_add_i32 s74, s83, s40
	v_lshl_add_u64 v[200:201], v[200:201], 0, s[46:47]
	s_mov_b32 m0, s74
	ds_read_b128 v[184:187], v159 offset:49152
	ds_read_b128 v[188:191], v159 offset:50176
	ds_read_b128 v[192:195], v159 offset:51200
	ds_read_b128 v[196:199], v159 offset:52224
	ds_read_b128 v[214:217], v159 offset:53248
	ds_read_b128 v[218:221], v159 offset:54272
	ds_read_b128 v[222:225], v159 offset:55296
	ds_read_b128 v[226:229], v159 offset:56320
	global_load_lds_dwordx4 v[200:201], off
	s_add_i32 m0, s74, 0x2000
	s_add_u32 s72, s72, 0x40080
	v_lshl_add_u64 v[200:201], v[230:231], 0, s[46:47]
	s_addc_u32 s73, s73, 0
	s_add_i32 s74, s86, s40
	global_load_lds_dwordx4 v[200:201], off
	v_lshl_add_u64 v[200:201], s[72:73], 0, v[146:147]
	s_mov_b32 m0, s74
	s_nop 0
	global_load_lds_dwordx4 v[200:201], off
	v_lshl_add_u64 v[200:201], s[72:73], 0, v[148:149]
	s_add_i32 m0, s74, 0x2000
	s_nop 0
	global_load_lds_dwordx4 v[200:201], off
	v_lshl_add_u64 v[200:201], v[232:233], 0, s[46:47]
	s_mov_b32 m0, s0
	s_nop 0
	global_load_lds_dwordx4 v[200:201], off
	v_lshl_add_u64 v[200:201], v[234:235], 0, s[46:47]
	s_mov_b32 m0, s2
	s_nop 0
	global_load_lds_dwordx4 v[200:201], off
	s_waitcnt vmcnt(8)
	s_waitcnt lgkmcnt(0)
	s_barrier
	s_setprio 1
	v_mfma_f32_16x16x32_bf16 v[68:71], v[132:135], v[184:187], v[68:71]
	v_mfma_f32_16x16x32_bf16 v[60:63], v[160:163], v[184:187], v[60:63]
	v_mfma_f32_16x16x32_bf16 v[48:51], v[132:135], v[192:195], v[48:51]
	v_mfma_f32_16x16x32_bf16 v[44:47], v[160:163], v[192:195], v[44:47]
	v_mfma_f32_16x16x32_bf16 v[32:35], v[132:135], v[214:217], v[32:35]
	v_mfma_f32_16x16x32_bf16 v[28:31], v[160:163], v[214:217], v[28:31]
	v_mfma_f32_16x16x32_bf16 v[16:19], v[132:135], v[222:225], v[16:19]
	v_mfma_f32_16x16x32_bf16 v[12:15], v[160:163], v[222:225], v[12:15]
	v_mfma_f32_16x16x32_bf16 v[68:71], v[140:143], v[188:191], v[68:71]
	v_mfma_f32_16x16x32_bf16 v[60:63], v[164:167], v[188:191], v[60:63]
	v_mfma_f32_16x16x32_bf16 v[48:51], v[140:143], v[196:199], v[48:51]
	v_mfma_f32_16x16x32_bf16 v[44:47], v[164:167], v[196:199], v[44:47]
	v_mfma_f32_16x16x32_bf16 v[32:35], v[140:143], v[218:221], v[32:35]
	v_mfma_f32_16x16x32_bf16 v[28:31], v[164:167], v[218:221], v[28:31]
	v_mfma_f32_16x16x32_bf16 v[16:19], v[140:143], v[226:229], v[16:19]
	v_mfma_f32_16x16x32_bf16 v[12:15], v[164:167], v[226:229], v[12:15]
	v_mfma_f32_16x16x32_bf16 v[56:59], v[168:171], v[184:187], v[56:59]
	v_mfma_f32_16x16x32_bf16 v[52:55], v[176:179], v[184:187], v[52:55]
	v_mfma_f32_16x16x32_bf16 v[40:43], v[168:171], v[192:195], v[40:43]
	v_mfma_f32_16x16x32_bf16 v[36:39], v[176:179], v[192:195], v[36:39]
	v_mfma_f32_16x16x32_bf16 v[24:27], v[168:171], v[214:217], v[24:27]
	v_mfma_f32_16x16x32_bf16 v[20:23], v[176:179], v[214:217], v[20:23]
	v_mfma_f32_16x16x32_bf16 v[8:11], v[168:171], v[222:225], v[8:11]
	v_mfma_f32_16x16x32_bf16 v[4:7], v[176:179], v[222:225], v[4:7]
	v_mfma_f32_16x16x32_bf16 v[56:59], v[172:175], v[188:191], v[56:59]
	v_mfma_f32_16x16x32_bf16 v[52:55], v[180:183], v[188:191], v[52:55]
	v_mfma_f32_16x16x32_bf16 v[40:43], v[172:175], v[196:199], v[40:43]
	v_mfma_f32_16x16x32_bf16 v[36:39], v[180:183], v[196:199], v[36:39]
	v_mfma_f32_16x16x32_bf16 v[24:27], v[172:175], v[218:221], v[24:27]
	v_mfma_f32_16x16x32_bf16 v[20:23], v[180:183], v[218:221], v[20:23]
	v_mfma_f32_16x16x32_bf16 v[8:11], v[172:175], v[226:229], v[8:11]
	v_mfma_f32_16x16x32_bf16 v[4:7], v[180:183], v[226:229], v[4:7]
	s_setprio 0
	s_barrier
	s_add_i32 s77, s77, 2
	s_add_u32 s70, s70, 0x100
	s_addc_u32 s71, s71, 0
	s_cmp_gt_u32 s77, 13
	s_cbranch_scc0 .LBB0_216
	s_add_u32 s70, s43, 0xffffff00
	s_addc_u32 s71, s44, -1
	s_andn2_b64 vcc, exec, s[6:7]
	s_cbranch_vccnz .LBB0_219
	v_mov_b32_e32 v4, 0
	s_mov_b32 s20, s28
	s_mov_b32 s18, s30
	s_mov_b64 s[8:9], s[36:37]
	s_mov_b32 s38, s33
	v_mov_b32_e32 v5, v4
	v_mov_b32_e32 v6, v4
	v_mov_b32_e32 v7, v4
	v_mov_b32_e32 v8, v4
	v_mov_b32_e32 v9, v4
	v_mov_b32_e32 v10, v4
	v_mov_b32_e32 v11, v4
	v_mov_b32_e32 v20, v4
	v_mov_b32_e32 v21, v4
	v_mov_b32_e32 v22, v4
	v_mov_b32_e32 v23, v4
	v_mov_b32_e32 v24, v4
	v_mov_b32_e32 v25, v4
	v_mov_b32_e32 v26, v4
	v_mov_b32_e32 v27, v4
	v_mov_b32_e32 v36, v4
	v_mov_b32_e32 v37, v4
	v_mov_b32_e32 v38, v4
	v_mov_b32_e32 v39, v4
	v_mov_b32_e32 v40, v4
	v_mov_b32_e32 v41, v4
	v_mov_b32_e32 v42, v4
	v_mov_b32_e32 v43, v4
	v_mov_b32_e32 v52, v4
	v_mov_b32_e32 v53, v4
	v_mov_b32_e32 v54, v4
	v_mov_b32_e32 v55, v4
	v_mov_b32_e32 v56, v4
	v_mov_b32_e32 v57, v4
	v_mov_b32_e32 v58, v4
	v_mov_b32_e32 v59, v4
	v_mov_b32_e32 v12, v4
	v_mov_b32_e32 v13, v4
	v_mov_b32_e32 v14, v4
	v_mov_b32_e32 v15, v4
	v_mov_b32_e32 v16, v4
	v_mov_b32_e32 v17, v4
	v_mov_b32_e32 v18, v4
	v_mov_b32_e32 v19, v4
	v_mov_b32_e32 v28, v4
	v_mov_b32_e32 v29, v4
	v_mov_b32_e32 v30, v4
	v_mov_b32_e32 v31, v4
	v_mov_b32_e32 v32, v4
	v_mov_b32_e32 v33, v4
	v_mov_b32_e32 v34, v4
	v_mov_b32_e32 v35, v4
	v_mov_b32_e32 v44, v4
	v_mov_b32_e32 v45, v4
	v_mov_b32_e32 v46, v4
	v_mov_b32_e32 v47, v4
	v_mov_b32_e32 v48, v4
	v_mov_b32_e32 v49, v4
	v_mov_b32_e32 v50, v4
	v_mov_b32_e32 v51, v4
	v_mov_b32_e32 v60, v4
	v_mov_b32_e32 v61, v4
	v_mov_b32_e32 v62, v4
	v_mov_b32_e32 v63, v4
	v_mov_b32_e32 v68, v4
	v_mov_b32_e32 v69, v4
	v_mov_b32_e32 v70, v4
	v_mov_b32_e32 v71, v4
	v_mov_b32_e32 v80, v4
	v_mov_b32_e32 v81, v4
	v_mov_b32_e32 v82, v4
	v_mov_b32_e32 v83, v4
	v_mov_b32_e32 v88, v4
	v_mov_b32_e32 v89, v4
	v_mov_b32_e32 v90, v4
	v_mov_b32_e32 v91, v4
	v_mov_b32_e32 v120, v4
	v_mov_b32_e32 v121, v4
	v_mov_b32_e32 v122, v4
	v_mov_b32_e32 v123, v4
	v_mov_b32_e32 v128, v4
	v_mov_b32_e32 v129, v4
	v_mov_b32_e32 v130, v4
	v_mov_b32_e32 v131, v4
	v_mov_b32_e32 v108, v4
	v_mov_b32_e32 v109, v4
	v_mov_b32_e32 v110, v4
	v_mov_b32_e32 v111, v4
	v_mov_b32_e32 v104, v4
	v_mov_b32_e32 v105, v4
	v_mov_b32_e32 v106, v4
	v_mov_b32_e32 v107, v4
	v_mov_b32_e32 v84, v4
	v_mov_b32_e32 v85, v4
	v_mov_b32_e32 v86, v4
	v_mov_b32_e32 v87, v4
	v_mov_b32_e32 v76, v4
	v_mov_b32_e32 v77, v4
	v_mov_b32_e32 v78, v4
	v_mov_b32_e32 v79, v4
	v_mov_b32_e32 v100, v4
	v_mov_b32_e32 v101, v4
	v_mov_b32_e32 v102, v4
	v_mov_b32_e32 v103, v4
	v_mov_b32_e32 v112, v4
	v_mov_b32_e32 v113, v4
	v_mov_b32_e32 v114, v4
	v_mov_b32_e32 v115, v4
	v_mov_b32_e32 v124, v4
	v_mov_b32_e32 v125, v4
	v_mov_b32_e32 v126, v4
	v_mov_b32_e32 v127, v4
	v_mov_b32_e32 v116, v4
	v_mov_b32_e32 v117, v4
	v_mov_b32_e32 v118, v4
	v_mov_b32_e32 v119, v4
	v_mov_b32_e32 v96, v4
	v_mov_b32_e32 v97, v4
	v_mov_b32_e32 v98, v4
	v_mov_b32_e32 v99, v4
	v_mov_b32_e32 v92, v4
	v_mov_b32_e32 v93, v4
	v_mov_b32_e32 v94, v4
	v_mov_b32_e32 v95, v4
	v_mov_b32_e32 v72, v4
	v_mov_b32_e32 v73, v4
	v_mov_b32_e32 v74, v4
	v_mov_b32_e32 v75, v4
	v_mov_b32_e32 v64, v4
	v_mov_b32_e32 v65, v4
	v_mov_b32_e32 v66, v4
	v_mov_b32_e32 v67, v4
	s_mov_b32 s83, 0x18000
	s_mov_b32 s86, 0x3fb8aa3b
	s_andn2_b64 vcc, exec, s[4:5]
	s_cbranch_vccnz .LBB0_220
	s_branch .LBB0_221

; #define PG8_STAGE(bufoff, gbase, voff) do { _Pragma("unroll") for (int _i = 0; _i < 2; ++_i) \
;         __builtin_amdgcn_global_load_lds((const unsigned*)((const char*)(gbase) + (voff)[_i]), (LAS unsigned*)(lds + (bufoff) + ldsw + _i * 8192), 16, 0, 0); } while (0)
; #define PG8_LDA(dst, b, h) do { _Pragma("unroll") for (int m = 0; m < 4; ++m) _Pragma("unroll") for (int k = 0; k < 2; ++k) dst[m][k] = *(const LAS bf16x8*)(lds + PG8_SA(b, h) + aoff + m * 2048 + k * 1024); } while (0)
; #define PG8_LDB(dst, b, h) do { _Pragma("unroll") for (int n = 0; n < 2; ++n) _Pragma("unroll") for (int k = 0; k < 2; ++k) dst[n][k] = *(const LAS bf16x8*)(lds + PG8_SB(b, h) + boff + n * 2048 + k * 1024); } while (0)
; #define PG8_MMA(ai, bj, At, Bt) do { __builtin_amdgcn_s_setprio(1); _Pragma("unroll") for (int m = 0; m < 4; ++m) _Pragma("unroll") for (int n = 0; n < 2; ++n) _Pragma("unroll") for (int k = 0; k < 2; ++k) \
;         acc[ai][bj][m][n] = __builtin_amdgcn_mfma_f32_16x16x32_bf16(Bt[n][k], At[m][k], acc[ai][bj][m][n], 0, 0, 0); __builtin_amdgcn_s_setprio(0); } while (0)
; #define PG8_WAIT_V(n) asm volatile("s_waitcnt vmcnt(" #n ")" ::: "memory")
; #define PG8_WAIT_L(n) asm volatile("s_waitcnt lgkmcnt(" #n ")" ::: "memory")
; #define PG8_BAR __builtin_amdgcn_s_barrier()
; #define PG8_SCHED __builtin_amdgcn_sched_barrier(0)
; template <class Epi>
; __device__ __forceinline__ void gemm_phase(LAS unsigned char* lds, const Gemm g, const int G, const int cidx, const Epi& E) {
;     ...
;             const char* a1 = cA + (size_t)(t + 1) * kstep;
;             const char* a2 = last ? nA : cA + (size_t)(t + 2) * kstep; const char* b2 = last ? nB : cB + (size_t)(t + 2) * kstep;
;             const char* a3 = a2 + kstep; const char* b3 = b2 + kstep;
;             PG8_LDB(B0, 0, 0); PG8_LDB(B1, 0, 1); PG8_SCHED; PG8_LDA(At, 0, 0); PG8_STAGE(PG8_SA(1, 1), a1 + hstep, voffA);
;             PG8_WAIT_V(8); PG8_WAIT_L(0); PG8_BAR; PG8_MMA(0, 0, At, B0); PG8_MMA(0, 1, At, B1); PG8_BAR; PG8_SCHED;
;             PG8_LDA(At, 0, 1); PG8_STAGE(PG8_SB(0, 0), b2, voffB); PG8_STAGE(PG8_SB(0, 1), b2 + hstep, voffB); PG8_STAGE(PG8_SA(0, 0), a2, voffA);
.LBB0_450:
	s_add_u32 s26, s10, s24
	s_addc_u32 s27, s11, s25
	s_add_u32 s26, s26, 0x100
	s_addc_u32 s27, s27, 0
	s_add_u32 s68, s43, s24
	s_addc_u32 s77, s44, s25
	s_add_i32 s83, 0, 0x10000
	s_cmpk_eq_i32 s24, 0x1500
	s_cselect_b32 s29, s21, s27
	s_cselect_b32 s28, s20, s26
	v_add_u32_e32 v3, s83, v157
	s_cselect_b32 s27, s9, s77
	s_cselect_b32 s26, s8, s68
	s_add_i32 s68, 0, 0x14000
	ds_read_b128 v[132:135], v3
	ds_read_b128 v[140:143], v3 offset:1024
	ds_read_b128 v[160:163], v3 offset:2048
	ds_read_b128 v[164:167], v3 offset:3072
	v_add_u32_e32 v3, s68, v157
	ds_read_b128 v[168:171], v3
	ds_read_b128 v[172:175], v3 offset:1024
	ds_read_b128 v[176:179], v3 offset:2048
	ds_read_b128 v[180:183], v3 offset:3072
	v_lshl_add_u64 v[200:201], v[154:155], 0, s[24:25]
	s_add_i32 m0, s71, 0xc000
	ds_read_b128 v[184:187], v159
	ds_read_b128 v[188:191], v159 offset:1024
	ds_read_b128 v[192:195], v159 offset:2048
	ds_read_b128 v[196:199], v159 offset:3072
	ds_read_b128 v[214:217], v159 offset:4096
	ds_read_b128 v[218:221], v159 offset:5120
	ds_read_b128 v[222:225], v159 offset:6144
	ds_read_b128 v[226:229], v159 offset:7168
	global_load_lds_dwordx4 v[200:201], off
	v_lshl_add_u64 v[200:201], v[0:1], 0, s[24:25]
	s_add_i32 m0, s71, 0xe000
	s_nop 0
	global_load_lds_dwordx4 v[200:201], off
	s_waitcnt vmcnt(8)
	s_waitcnt lgkmcnt(0)
	s_barrier
	s_setprio 1
	v_mfma_f32_16x16x32_bf16 v[100:103], v[132:135], v[184:187], v[100:103]
	v_mfma_f32_16x16x32_bf16 v[108:111], v[160:163], v[184:187], v[108:111]
	v_mfma_f32_16x16x32_bf16 v[120:123], v[132:135], v[192:195], v[120:123]
	v_mfma_f32_16x16x32_bf16 v[128:131], v[160:163], v[192:195], v[128:131]
	v_mfma_f32_16x16x32_bf16 v[96:99], v[132:135], v[214:217], v[96:99]
	v_mfma_f32_16x16x32_bf16 v[92:95], v[160:163], v[214:217], v[92:95]
	v_mfma_f32_16x16x32_bf16 v[80:83], v[132:135], v[222:225], v[80:83]
	v_mfma_f32_16x16x32_bf16 v[76:79], v[160:163], v[222:225], v[76:79]
	v_mfma_f32_16x16x32_bf16 v[100:103], v[140:143], v[188:191], v[100:103]
	v_mfma_f32_16x16x32_bf16 v[108:111], v[164:167], v[188:191], v[108:111]
	v_mfma_f32_16x16x32_bf16 v[120:123], v[140:143], v[196:199], v[120:123]
	v_mfma_f32_16x16x32_bf16 v[128:131], v[164:167], v[196:199], v[128:131]
	v_mfma_f32_16x16x32_bf16 v[96:99], v[140:143], v[218:221], v[96:99]
	v_mfma_f32_16x16x32_bf16 v[92:95], v[164:167], v[218:221], v[92:95]
	v_mfma_f32_16x16x32_bf16 v[80:83], v[140:143], v[226:229], v[80:83]
	v_mfma_f32_16x16x32_bf16 v[76:79], v[164:167], v[226:229], v[76:79]
	v_mfma_f32_16x16x32_bf16 v[116:119], v[168:171], v[184:187], v[116:119]
	v_mfma_f32_16x16x32_bf16 v[124:127], v[176:179], v[184:187], v[124:127]
	v_mfma_f32_16x16x32_bf16 v[112:115], v[168:171], v[192:195], v[112:115]
	v_mfma_f32_16x16x32_bf16 v[104:107], v[176:179], v[192:195], v[104:107]
	v_mfma_f32_16x16x32_bf16 v[88:91], v[168:171], v[214:217], v[88:91]
	v_mfma_f32_16x16x32_bf16 v[84:87], v[176:179], v[214:217], v[84:87]
	v_mfma_f32_16x16x32_bf16 v[72:75], v[168:171], v[222:225], v[72:75]
	v_mfma_f32_16x16x32_bf16 v[68:71], v[176:179], v[222:225], v[68:71]
	v_mfma_f32_16x16x32_bf16 v[116:119], v[172:175], v[188:191], v[116:119]
	v_mfma_f32_16x16x32_bf16 v[124:127], v[180:183], v[188:191], v[124:127]
	v_mfma_f32_16x16x32_bf16 v[112:115], v[172:175], v[196:199], v[112:115]
	v_mfma_f32_16x16x32_bf16 v[104:107], v[180:183], v[196:199], v[104:107]
	v_mfma_f32_16x16x32_bf16 v[88:91], v[172:175], v[218:221], v[88:91]
	v_mfma_f32_16x16x32_bf16 v[84:87], v[180:183], v[218:221], v[84:87]
	v_mfma_f32_16x16x32_bf16 v[72:75], v[172:175], v[226:229], v[72:75]
	v_mfma_f32_16x16x32_bf16 v[68:71], v[180:183], v[226:229], v[68:71]
	s_setprio 0
	s_barrier
	s_add_i32 s77, s83, s70
	v_lshl_add_u64 v[200:201], s[26:27], 0, v[146:147]
	s_mov_b32 m0, s77
	ds_read_b128 v[184:187], v159 offset:16384
	ds_read_b128 v[188:191], v159 offset:17408
	ds_read_b128 v[192:195], v159 offset:18432
	ds_read_b128 v[196:199], v159 offset:19456
	ds_read_b128 v[214:217], v159 offset:20480
	ds_read_b128 v[218:221], v159 offset:21504
	ds_read_b128 v[222:225], v159 offset:22528
	ds_read_b128 v[226:229], v159 offset:23552
	global_load_lds_dwordx4 v[200:201], off
	s_add_i32 m0, s77, 0x2000
	s_add_u32 s86, s26, 0xb0000
	v_lshl_add_u64 v[230:231], s[26:27], 0, v[148:149]
	s_addc_u32 s87, s27, 0
	s_add_i32 s68, s68, s70
	global_load_lds_dwordx4 v[230:231], off
	v_lshl_add_u64 v[232:233], s[86:87], 0, v[146:147]
	s_mov_b32 m0, s68
	v_lshl_add_u64 v[234:235], s[28:29], 0, v[148:149]
	global_load_lds_dwordx4 v[232:233], off
	v_lshl_add_u64 v[232:233], s[86:87], 0, v[148:149]
	s_add_i32 m0, s68, 0x2000
	s_nop 0
	global_load_lds_dwordx4 v[232:233], off
	v_lshl_add_u64 v[232:233], s[28:29], 0, v[146:147]
	s_mov_b32 m0, s71
	s_nop 0
	global_load_lds_dwordx4 v[232:233], off
	s_mov_b32 m0, s72
	s_nop 0
	global_load_lds_dwordx4 v[234:235], off
	s_waitcnt vmcnt(8)
	s_waitcnt lgkmcnt(0)
	s_barrier
; #define PG8_STAGE(bufoff, gbase, voff) do { _Pragma("unroll") for (int _i = 0; _i < 2; ++_i) \
;         __builtin_amdgcn_global_load_lds((const unsigned*)((const char*)(gbase) + (voff)[_i]), (LAS unsigned*)(lds + (bufoff) + ldsw + _i * 8192), 16, 0, 0); } while (0)
; #define PG8_LDA(dst, b, h) do { _Pragma("unroll") for (int m = 0; m < 4; ++m) _Pragma("unroll") for (int k = 0; k < 2; ++k) dst[m][k] = *(const LAS bf16x8*)(lds + PG8_SA(b, h) + aoff + m * 2048 + k * 1024); } while (0)
; #define PG8_LDB(dst, b, h) do { _Pragma("unroll") for (int n = 0; n < 2; ++n) _Pragma("unroll") for (int k = 0; k < 2; ++k) dst[n][k] = *(const LAS bf16x8*)(lds + PG8_SB(b, h) + boff + n * 2048 + k * 1024); } while (0)
; #define PG8_MMA(ai, bj, At, Bt) do { __builtin_amdgcn_s_setprio(1); _Pragma("unroll") for (int m = 0; m < 4; ++m) _Pragma("unroll") for (int n = 0; n < 2; ++n) _Pragma("unroll") for (int k = 0; k < 2; ++k) \
;         acc[ai][bj][m][n] = __builtin_amdgcn_mfma_f32_16x16x32_bf16(Bt[n][k], At[m][k], acc[ai][bj][m][n], 0, 0, 0); __builtin_amdgcn_s_setprio(0); } while (0)
; #define PG8_WAIT_V(n) asm volatile("s_waitcnt vmcnt(" #n ")" ::: "memory")
; #define PG8_WAIT_L(n) asm volatile("s_waitcnt lgkmcnt(" #n ")" ::: "memory")
; #define PG8_BAR __builtin_amdgcn_s_barrier()
; #define PG8_SCHED __builtin_amdgcn_sched_barrier(0)
; template <class Epi>
; __device__ __forceinline__ void gemm_phase(LAS unsigned char* lds, const Gemm g, const int G, const int cidx, const Epi& E) {
;     ...
;             PG8_WAIT_V(8); PG8_WAIT_L(0); PG8_BAR; PG8_MMA(1, 0, At, B0); PG8_MMA(1, 1, At, B1); PG8_BAR; PG8_SCHED;
;             PG8_LDB(B0, 1, 0); PG8_LDB(B1, 1, 1); PG8_SCHED; PG8_LDA(At, 1, 0); PG8_STAGE(PG8_SA(0, 1), a2 + hstep, voffA);
;             PG8_WAIT_V(8); PG8_WAIT_L(0); PG8_BAR; PG8_MMA(0, 0, At, B0); PG8_MMA(0, 1, At, B1); PG8_BAR; PG8_SCHED;
	s_setprio 1
	v_mfma_f32_16x16x32_bf16 v[64:67], v[132:135], v[184:187], v[64:67]
	v_mfma_f32_16x16x32_bf16 v[60:63], v[160:163], v[184:187], v[60:63]
	v_mfma_f32_16x16x32_bf16 v[48:51], v[132:135], v[192:195], v[48:51]
	v_mfma_f32_16x16x32_bf16 v[44:47], v[160:163], v[192:195], v[44:47]
	v_mfma_f32_16x16x32_bf16 v[32:35], v[132:135], v[214:217], v[32:35]
	v_mfma_f32_16x16x32_bf16 v[28:31], v[160:163], v[214:217], v[28:31]
	v_mfma_f32_16x16x32_bf16 v[16:19], v[132:135], v[222:225], v[16:19]
	v_mfma_f32_16x16x32_bf16 v[12:15], v[160:163], v[222:225], v[12:15]
	v_mfma_f32_16x16x32_bf16 v[64:67], v[140:143], v[188:191], v[64:67]
	v_mfma_f32_16x16x32_bf16 v[60:63], v[164:167], v[188:191], v[60:63]
	v_mfma_f32_16x16x32_bf16 v[48:51], v[140:143], v[196:199], v[48:51]
	v_mfma_f32_16x16x32_bf16 v[44:47], v[164:167], v[196:199], v[44:47]
	v_mfma_f32_16x16x32_bf16 v[32:35], v[140:143], v[218:221], v[32:35]
	v_mfma_f32_16x16x32_bf16 v[28:31], v[164:167], v[218:221], v[28:31]
	v_mfma_f32_16x16x32_bf16 v[16:19], v[140:143], v[226:229], v[16:19]
	v_mfma_f32_16x16x32_bf16 v[12:15], v[164:167], v[226:229], v[12:15]
	v_mfma_f32_16x16x32_bf16 v[56:59], v[168:171], v[184:187], v[56:59]
	v_mfma_f32_16x16x32_bf16 v[52:55], v[176:179], v[184:187], v[52:55]
	v_mfma_f32_16x16x32_bf16 v[40:43], v[168:171], v[192:195], v[40:43]
	v_mfma_f32_16x16x32_bf16 v[36:39], v[176:179], v[192:195], v[36:39]
	v_mfma_f32_16x16x32_bf16 v[24:27], v[168:171], v[214:217], v[24:27]
	v_mfma_f32_16x16x32_bf16 v[20:23], v[176:179], v[214:217], v[20:23]
	v_mfma_f32_16x16x32_bf16 v[8:11], v[168:171], v[222:225], v[8:11]
	v_mfma_f32_16x16x32_bf16 v[4:7], v[176:179], v[222:225], v[4:7]
	v_mfma_f32_16x16x32_bf16 v[56:59], v[172:175], v[188:191], v[56:59]
	v_mfma_f32_16x16x32_bf16 v[52:55], v[180:183], v[188:191], v[52:55]
	v_mfma_f32_16x16x32_bf16 v[40:43], v[172:175], v[196:199], v[40:43]
	v_mfma_f32_16x16x32_bf16 v[36:39], v[180:183], v[196:199], v[36:39]
	v_mfma_f32_16x16x32_bf16 v[24:27], v[172:175], v[218:221], v[24:27]
	v_mfma_f32_16x16x32_bf16 v[20:23], v[180:183], v[218:221], v[20:23]
	v_mfma_f32_16x16x32_bf16 v[8:11], v[172:175], v[226:229], v[8:11]
	v_mfma_f32_16x16x32_bf16 v[4:7], v[180:183], v[226:229], v[4:7]
	s_setprio 0
	s_barrier
	s_add_i32 s68, 0, 0x18000
	v_add_u32_e32 v3, s68, v157
	s_add_i32 s77, 0, 0x1c000
	ds_read_b128 v[132:135], v3
	ds_read_b128 v[140:143], v3 offset:1024
	ds_read_b128 v[160:163], v3 offset:2048
	ds_read_b128 v[164:167], v3 offset:3072
	v_add_u32_e32 v3, s77, v157
	ds_read_b128 v[168:171], v3
	ds_read_b128 v[172:175], v3 offset:1024
	ds_read_b128 v[176:179], v3 offset:2048
	ds_read_b128 v[180:183], v3 offset:3072
	s_add_u32 s28, s28, 0xb0000
	s_addc_u32 s29, s29, 0
	s_mov_b32 m0, s73
	v_lshl_add_u64 v[236:237], s[28:29], 0, v[146:147]
	ds_read_b128 v[184:187], v159 offset:32768
	ds_read_b128 v[188:191], v159 offset:33792
	ds_read_b128 v[192:195], v159 offset:34816
	ds_read_b128 v[196:199], v159 offset:35840
	ds_read_b128 v[214:217], v159 offset:36864
	ds_read_b128 v[218:221], v159 offset:37888
	ds_read_b128 v[222:225], v159 offset:38912
	ds_read_b128 v[226:229], v159 offset:39936
	global_load_lds_dwordx4 v[236:237], off
	v_lshl_add_u64 v[236:237], s[28:29], 0, v[148:149]
	s_mov_b32 m0, s74
	s_nop 0
	global_load_lds_dwordx4 v[236:237], off
	s_waitcnt vmcnt(8)
	s_waitcnt lgkmcnt(0)
	s_barrier
	s_setprio 1
	v_mfma_f32_16x16x32_bf16 v[100:103], v[132:135], v[184:187], v[100:103]
	v_mfma_f32_16x16x32_bf16 v[108:111], v[160:163], v[184:187], v[108:111]
	v_mfma_f32_16x16x32_bf16 v[120:123], v[132:135], v[192:195], v[120:123]
	v_mfma_f32_16x16x32_bf16 v[128:131], v[160:163], v[192:195], v[128:131]
	v_mfma_f32_16x16x32_bf16 v[96:99], v[132:135], v[214:217], v[96:99]
	v_mfma_f32_16x16x32_bf16 v[92:95], v[160:163], v[214:217], v[92:95]
	v_mfma_f32_16x16x32_bf16 v[80:83], v[132:135], v[222:225], v[80:83]
	v_mfma_f32_16x16x32_bf16 v[76:79], v[160:163], v[222:225], v[76:79]
	v_mfma_f32_16x16x32_bf16 v[100:103], v[140:143], v[188:191], v[100:103]
	v_mfma_f32_16x16x32_bf16 v[108:111], v[164:167], v[188:191], v[108:111]
	v_mfma_f32_16x16x32_bf16 v[120:123], v[140:143], v[196:199], v[120:123]
	v_mfma_f32_16x16x32_bf16 v[128:131], v[164:167], v[196:199], v[128:131]
	v_mfma_f32_16x16x32_bf16 v[96:99], v[140:143], v[218:221], v[96:99]
	v_mfma_f32_16x16x32_bf16 v[92:95], v[164:167], v[218:221], v[92:95]
	v_mfma_f32_16x16x32_bf16 v[80:83], v[140:143], v[226:229], v[80:83]
	v_mfma_f32_16x16x32_bf16 v[76:79], v[164:167], v[226:229], v[76:79]
	v_mfma_f32_16x16x32_bf16 v[116:119], v[168:171], v[184:187], v[116:119]
	v_mfma_f32_16x16x32_bf16 v[124:127], v[176:179], v[184:187], v[124:127]
	v_mfma_f32_16x16x32_bf16 v[112:115], v[168:171], v[192:195], v[112:115]
	v_mfma_f32_16x16x32_bf16 v[104:107], v[176:179], v[192:195], v[104:107]
	v_mfma_f32_16x16x32_bf16 v[88:91], v[168:171], v[214:217], v[88:91]
	v_mfma_f32_16x16x32_bf16 v[84:87], v[176:179], v[214:217], v[84:87]
	v_mfma_f32_16x16x32_bf16 v[72:75], v[168:171], v[222:225], v[72:75]
	v_mfma_f32_16x16x32_bf16 v[68:71], v[176:179], v[222:225], v[68:71]
	v_mfma_f32_16x16x32_bf16 v[116:119], v[172:175], v[188:191], v[116:119]
	v_mfma_f32_16x16x32_bf16 v[124:127], v[180:183], v[188:191], v[124:127]
	v_mfma_f32_16x16x32_bf16 v[112:115], v[172:175], v[196:199], v[112:115]
	v_mfma_f32_16x16x32_bf16 v[104:107], v[180:183], v[196:199], v[104:107]
	v_mfma_f32_16x16x32_bf16 v[88:91], v[172:175], v[218:221], v[88:91]
	v_mfma_f32_16x16x32_bf16 v[84:87], v[180:183], v[218:221], v[84:87]
	v_mfma_f32_16x16x32_bf16 v[72:75], v[172:175], v[226:229], v[72:75]
	v_mfma_f32_16x16x32_bf16 v[68:71], v[180:183], v[226:229], v[68:71]
	s_setprio 0
	s_barrier
; #define PG8_STAGE(bufoff, gbase, voff) do { _Pragma("unroll") for (int _i = 0; _i < 2; ++_i) \
;         __builtin_amdgcn_global_load_lds((const unsigned*)((const char*)(gbase) + (voff)[_i]), (LAS unsigned*)(lds + (bufoff) + ldsw + _i * 8192), 16, 0, 0); } while (0)
; #define PG8_LDA(dst, b, h) do { _Pragma("unroll") for (int m = 0; m < 4; ++m) _Pragma("unroll") for (int k = 0; k < 2; ++k) dst[m][k] = *(const LAS bf16x8*)(lds + PG8_SA(b, h) + aoff + m * 2048 + k * 1024); } while (0)
; #define PG8_MMA(ai, bj, At, Bt) do { __builtin_amdgcn_s_setprio(1); _Pragma("unroll") for (int m = 0; m < 4; ++m) _Pragma("unroll") for (int n = 0; n < 2; ++n) _Pragma("unroll") for (int k = 0; k < 2; ++k) \
;         acc[ai][bj][m][n] = __builtin_amdgcn_mfma_f32_16x16x32_bf16(Bt[n][k], At[m][k], acc[ai][bj][m][n], 0, 0, 0); __builtin_amdgcn_s_setprio(0); } while (0)
; #define PG8_WAIT_V(n) asm volatile("s_waitcnt vmcnt(" #n ")" ::: "memory")
; #define PG8_WAIT_L(n) asm volatile("s_waitcnt lgkmcnt(" #n ")" ::: "memory")
; #define PG8_BAR __builtin_amdgcn_s_barrier()
; #define PG8_SCHED __builtin_amdgcn_sched_barrier(0)
; template <class Epi>
; __device__ __forceinline__ void gemm_phase(LAS unsigned char* lds, const Gemm g, const int G, const int cidx, const Epi& E) {
;     ...
;             PG8_LDA(At, 1, 1); PG8_STAGE(PG8_SB(1, 0), b3, voffB); PG8_STAGE(PG8_SB(1, 1), b3 + hstep, voffB); PG8_STAGE(PG8_SA(1, 0), a3, voffA);
;             PG8_WAIT_V(8); PG8_WAIT_L(0); PG8_BAR; PG8_MMA(1, 0, At, B0); PG8_MMA(1, 1, At, B1); PG8_BAR; PG8_SCHED;
;         }
;         if constexpr (!Epi::AFTER_DRAIN) E(acc, cur, wr, wc, fr, fq);
;         if (!has_next) break;
; #pragma unroll
;         for (int a = 0; a < 2; ++a)
; #pragma unroll
;             for (int b = 0; b < 2; ++b)
; #pragma unroll
;                 for (int m = 0; m < 4; ++m)
; #pragma unroll
;                     for (int n = 0; n < 2; ++n) acc[a][b][m][n] = ZERO4;
;         cur = nxt; cA = nA; cB = nB; ++ui;
	s_add_i32 s28, s68, s70
	v_lshl_add_u64 v[200:201], v[200:201], 0, s[46:47]
	s_mov_b32 m0, s28
	ds_read_b128 v[184:187], v159 offset:49152
	ds_read_b128 v[188:191], v159 offset:50176
	ds_read_b128 v[192:195], v159 offset:51200
	ds_read_b128 v[196:199], v159 offset:52224
	ds_read_b128 v[214:217], v159 offset:53248
	ds_read_b128 v[218:221], v159 offset:54272
	ds_read_b128 v[222:225], v159 offset:55296
	ds_read_b128 v[226:229], v159 offset:56320
	global_load_lds_dwordx4 v[200:201], off
	s_add_i32 m0, s28, 0x2000
	s_add_u32 s26, s26, 0xb0080
	v_lshl_add_u64 v[200:201], v[230:231], 0, s[46:47]
	s_addc_u32 s27, s27, 0
	s_add_i32 s28, s77, s70
	global_load_lds_dwordx4 v[200:201], off
	v_lshl_add_u64 v[200:201], s[26:27], 0, v[146:147]
	s_mov_b32 m0, s28
	s_nop 0
	global_load_lds_dwordx4 v[200:201], off
	v_lshl_add_u64 v[200:201], s[26:27], 0, v[148:149]
	s_add_i32 m0, s28, 0x2000
	s_nop 0
	global_load_lds_dwordx4 v[200:201], off
	v_lshl_add_u64 v[200:201], v[232:233], 0, s[46:47]
	s_mov_b32 m0, s75
	s_nop 0
	global_load_lds_dwordx4 v[200:201], off
	v_lshl_add_u64 v[200:201], v[234:235], 0, s[46:47]
	s_mov_b32 m0, s76
	s_nop 0
	global_load_lds_dwordx4 v[200:201], off
	s_waitcnt vmcnt(8)
	s_waitcnt lgkmcnt(0)
	s_barrier
	s_setprio 1
	v_mfma_f32_16x16x32_bf16 v[64:67], v[132:135], v[184:187], v[64:67]
	v_mfma_f32_16x16x32_bf16 v[60:63], v[160:163], v[184:187], v[60:63]
	v_mfma_f32_16x16x32_bf16 v[48:51], v[132:135], v[192:195], v[48:51]
	v_mfma_f32_16x16x32_bf16 v[44:47], v[160:163], v[192:195], v[44:47]
	v_mfma_f32_16x16x32_bf16 v[32:35], v[132:135], v[214:217], v[32:35]
	v_mfma_f32_16x16x32_bf16 v[28:31], v[160:163], v[214:217], v[28:31]
	v_mfma_f32_16x16x32_bf16 v[16:19], v[132:135], v[222:225], v[16:19]
	v_mfma_f32_16x16x32_bf16 v[12:15], v[160:163], v[222:225], v[12:15]
	v_mfma_f32_16x16x32_bf16 v[64:67], v[140:143], v[188:191], v[64:67]
	v_mfma_f32_16x16x32_bf16 v[60:63], v[164:167], v[188:191], v[60:63]
	v_mfma_f32_16x16x32_bf16 v[48:51], v[140:143], v[196:199], v[48:51]
	v_mfma_f32_16x16x32_bf16 v[44:47], v[164:167], v[196:199], v[44:47]
	v_mfma_f32_16x16x32_bf16 v[32:35], v[140:143], v[218:221], v[32:35]
	v_mfma_f32_16x16x32_bf16 v[28:31], v[164:167], v[218:221], v[28:31]
	v_mfma_f32_16x16x32_bf16 v[16:19], v[140:143], v[226:229], v[16:19]
	v_mfma_f32_16x16x32_bf16 v[12:15], v[164:167], v[226:229], v[12:15]
	v_mfma_f32_16x16x32_bf16 v[56:59], v[168:171], v[184:187], v[56:59]
	v_mfma_f32_16x16x32_bf16 v[52:55], v[176:179], v[184:187], v[52:55]
	v_mfma_f32_16x16x32_bf16 v[40:43], v[168:171], v[192:195], v[40:43]
	v_mfma_f32_16x16x32_bf16 v[36:39], v[176:179], v[192:195], v[36:39]
	v_mfma_f32_16x16x32_bf16 v[24:27], v[168:171], v[214:217], v[24:27]
	v_mfma_f32_16x16x32_bf16 v[20:23], v[176:179], v[214:217], v[20:23]
	v_mfma_f32_16x16x32_bf16 v[8:11], v[168:171], v[222:225], v[8:11]
	v_mfma_f32_16x16x32_bf16 v[4:7], v[176:179], v[222:225], v[4:7]
	v_mfma_f32_16x16x32_bf16 v[56:59], v[172:175], v[188:191], v[56:59]
	v_mfma_f32_16x16x32_bf16 v[52:55], v[180:183], v[188:191], v[52:55]
	v_mfma_f32_16x16x32_bf16 v[40:43], v[172:175], v[196:199], v[40:43]
	v_mfma_f32_16x16x32_bf16 v[36:39], v[180:183], v[196:199], v[36:39]
	v_mfma_f32_16x16x32_bf16 v[24:27], v[172:175], v[218:221], v[24:27]
	v_mfma_f32_16x16x32_bf16 v[20:23], v[180:183], v[218:221], v[20:23]
	v_mfma_f32_16x16x32_bf16 v[8:11], v[172:175], v[226:229], v[8:11]
	v_mfma_f32_16x16x32_bf16 v[4:7], v[180:183], v[226:229], v[4:7]
	s_setprio 0
	s_barrier
	s_add_i32 s45, s45, 2
	s_add_u32 s24, s24, 0x100
	s_addc_u32 s25, s25, 0
	s_cmp_gt_u32 s45, 41
	s_cbranch_scc0 .LBB0_450
	s_add_u32 s24, s43, 0xffffff00
	s_addc_u32 s25, s44, -1
	s_and_b64 vcc, exec, s[6:7]
	s_cbranch_vccnz .LBB0_453
	v_mov_b32_e32 v4, 0
	s_mov_b32 s14, s84
	s_mov_b32 s35, s88
	s_mov_b64 s[10:11], s[20:21]
	s_mov_b32 s79, s33
	v_mov_b32_e32 v5, v4
	v_mov_b32_e32 v6, v4
	v_mov_b32_e32 v7, v4
	v_mov_b32_e32 v8, v4
	v_mov_b32_e32 v9, v4
	v_mov_b32_e32 v10, v4
	v_mov_b32_e32 v11, v4
	v_mov_b32_e32 v20, v4
	v_mov_b32_e32 v21, v4
	v_mov_b32_e32 v22, v4
	v_mov_b32_e32 v23, v4
	v_mov_b32_e32 v24, v4
	v_mov_b32_e32 v25, v4
	v_mov_b32_e32 v26, v4
	v_mov_b32_e32 v27, v4
	v_mov_b32_e32 v36, v4
	v_mov_b32_e32 v37, v4
	v_mov_b32_e32 v38, v4
	v_mov_b32_e32 v39, v4
	v_mov_b32_e32 v40, v4
	v_mov_b32_e32 v41, v4
	v_mov_b32_e32 v42, v4
	v_mov_b32_e32 v43, v4
	v_mov_b32_e32 v52, v4
	v_mov_b32_e32 v53, v4
	v_mov_b32_e32 v54, v4
	v_mov_b32_e32 v55, v4
	v_mov_b32_e32 v56, v4
	v_mov_b32_e32 v57, v4
	v_mov_b32_e32 v58, v4
	v_mov_b32_e32 v59, v4
	v_mov_b32_e32 v12, v4
	v_mov_b32_e32 v13, v4
	v_mov_b32_e32 v14, v4
	v_mov_b32_e32 v15, v4
	v_mov_b32_e32 v16, v4
	v_mov_b32_e32 v17, v4
	v_mov_b32_e32 v18, v4
	v_mov_b32_e32 v19, v4
	v_mov_b32_e32 v28, v4
	v_mov_b32_e32 v29, v4
	v_mov_b32_e32 v30, v4
	v_mov_b32_e32 v31, v4
	v_mov_b32_e32 v32, v4
	v_mov_b32_e32 v33, v4
	v_mov_b32_e32 v34, v4
	v_mov_b32_e32 v35, v4
	v_mov_b32_e32 v44, v4
	v_mov_b32_e32 v45, v4
	v_mov_b32_e32 v46, v4
	v_mov_b32_e32 v47, v4
	v_mov_b32_e32 v48, v4
	v_mov_b32_e32 v49, v4
	v_mov_b32_e32 v50, v4
	v_mov_b32_e32 v51, v4
	v_mov_b32_e32 v60, v4
	v_mov_b32_e32 v61, v4
	v_mov_b32_e32 v62, v4
	v_mov_b32_e32 v63, v4
	v_mov_b32_e32 v64, v4
	v_mov_b32_e32 v65, v4
	v_mov_b32_e32 v66, v4
	v_mov_b32_e32 v67, v4
	v_mov_b32_e32 v68, v4
	v_mov_b32_e32 v69, v4
	v_mov_b32_e32 v70, v4
	v_mov_b32_e32 v71, v4
	v_mov_b32_e32 v72, v4
	v_mov_b32_e32 v73, v4
	v_mov_b32_e32 v74, v4
	v_mov_b32_e32 v75, v4
	v_mov_b32_e32 v84, v4
	v_mov_b32_e32 v85, v4
	v_mov_b32_e32 v86, v4
	v_mov_b32_e32 v87, v4
	v_mov_b32_e32 v88, v4
	v_mov_b32_e32 v89, v4
	v_mov_b32_e32 v90, v4
	v_mov_b32_e32 v91, v4
	v_mov_b32_e32 v104, v4
	v_mov_b32_e32 v105, v4
	v_mov_b32_e32 v106, v4
	v_mov_b32_e32 v107, v4
	v_mov_b32_e32 v112, v4
	v_mov_b32_e32 v113, v4
	v_mov_b32_e32 v114, v4
	v_mov_b32_e32 v115, v4
	v_mov_b32_e32 v124, v4
	v_mov_b32_e32 v125, v4
	v_mov_b32_e32 v126, v4
	v_mov_b32_e32 v127, v4
	v_mov_b32_e32 v116, v4
	v_mov_b32_e32 v117, v4
	v_mov_b32_e32 v118, v4
	v_mov_b32_e32 v119, v4
	v_mov_b32_e32 v76, v4
	v_mov_b32_e32 v77, v4
	v_mov_b32_e32 v78, v4
	v_mov_b32_e32 v79, v4
	v_mov_b32_e32 v80, v4
	v_mov_b32_e32 v81, v4
	v_mov_b32_e32 v82, v4
	v_mov_b32_e32 v83, v4
	v_mov_b32_e32 v92, v4
	v_mov_b32_e32 v93, v4
	v_mov_b32_e32 v94, v4
	v_mov_b32_e32 v95, v4
	v_mov_b32_e32 v96, v4
	v_mov_b32_e32 v97, v4
	v_mov_b32_e32 v98, v4
	v_mov_b32_e32 v99, v4
	v_mov_b32_e32 v128, v4
	v_mov_b32_e32 v129, v4
	v_mov_b32_e32 v130, v4
	v_mov_b32_e32 v131, v4
	v_mov_b32_e32 v120, v4
	v_mov_b32_e32 v121, v4
	v_mov_b32_e32 v122, v4
	v_mov_b32_e32 v123, v4
	v_mov_b32_e32 v108, v4
	v_mov_b32_e32 v109, v4
	v_mov_b32_e32 v110, v4
	v_mov_b32_e32 v111, v4
	v_mov_b32_e32 v100, v4
	v_mov_b32_e32 v101, v4
	v_mov_b32_e32 v102, v4
	v_mov_b32_e32 v103, v4
	s_mov_b32 s83, 0x18000
	s_mov_b32 s86, 0x3fb8aa3b
	s_andn2_b64 vcc, exec, s[4:5]
	s_cbranch_vccnz .LBB0_454
	s_branch .LBB0_455

; #define PG8_STAGE(bufoff, gbase, voff) do { _Pragma("unroll") for (int _i = 0; _i < 2; ++_i) \
;         __builtin_amdgcn_global_load_lds((const unsigned*)((const char*)(gbase) + (voff)[_i]), (LAS unsigned*)(lds + (bufoff) + ldsw + _i * 8192), 16, 0, 0); } while (0)
; #define PG8_LDA(dst, b, h) do { _Pragma("unroll") for (int m = 0; m < 4; ++m) _Pragma("unroll") for (int k = 0; k < 2; ++k) dst[m][k] = *(const LAS bf16x8*)(lds + PG8_SA(b, h) + aoff + m * 2048 + k * 1024); } while (0)
; #define PG8_LDB(dst, b, h) do { _Pragma("unroll") for (int n = 0; n < 2; ++n) _Pragma("unroll") for (int k = 0; k < 2; ++k) dst[n][k] = *(const LAS bf16x8*)(lds + PG8_SB(b, h) + boff + n * 2048 + k * 1024); } while (0)
; #define PG8_MMA(ai, bj, At, Bt) do { __builtin_amdgcn_s_setprio(1); _Pragma("unroll") for (int m = 0; m < 4; ++m) _Pragma("unroll") for (int n = 0; n < 2; ++n) _Pragma("unroll") for (int k = 0; k < 2; ++k) \
;         acc[ai][bj][m][n] = __builtin_amdgcn_mfma_f32_16x16x32_bf16(Bt[n][k], At[m][k], acc[ai][bj][m][n], 0, 0, 0); __builtin_amdgcn_s_setprio(0); } while (0)
; #define PG8_WAIT_V(n) asm volatile("s_waitcnt vmcnt(" #n ")" ::: "memory")
; #define PG8_WAIT_L(n) asm volatile("s_waitcnt lgkmcnt(" #n ")" ::: "memory")
; #define PG8_BAR __builtin_amdgcn_s_barrier()
; #define PG8_SCHED __builtin_amdgcn_sched_barrier(0)
; template <class Epi>
; __device__ __forceinline__ void gemm_phase(LAS unsigned char* lds, const Gemm g, const int G, const int cidx, const Epi& E) {
;     ...
;             const char* a1 = cA + (size_t)(t + 1) * kstep;
;             const char* a2 = last ? nA : cA + (size_t)(t + 2) * kstep; const char* b2 = last ? nB : cB + (size_t)(t + 2) * kstep;
;             const char* a3 = a2 + kstep; const char* b3 = b2 + kstep;
;             PG8_LDB(B0, 0, 0); PG8_LDB(B1, 0, 1); PG8_SCHED; PG8_LDA(At, 0, 0); PG8_STAGE(PG8_SA(1, 1), a1 + hstep, voffA);
;             PG8_WAIT_V(8); PG8_WAIT_L(0); PG8_BAR; PG8_MMA(0, 0, At, B0); PG8_MMA(0, 1, At, B1); PG8_BAR; PG8_SCHED;
;             PG8_LDA(At, 0, 1); PG8_STAGE(PG8_SB(0, 0), b2, voffB); PG8_STAGE(PG8_SB(0, 1), b2 + hstep, voffB); PG8_STAGE(PG8_SA(0, 0), a2, voffA);
.LBB0_601:
	s_add_u32 s24, s20, 0xfffc0080
	s_addc_u32 s25, s21, -1
	s_add_i32 s43, 0, 0x10000
	s_cmp_eq_u32 s45, 12
	s_cselect_b32 s27, s11, s25
	s_cselect_b32 s26, s19, s24
	v_add_u32_e32 v132, s43, v145
	s_cselect_b32 s25, s9, s44
	s_cselect_b32 s24, s33, s42
	s_add_i32 s68, 0, 0x14000
	ds_read_b128 v[158:161], v132
	ds_read_b128 v[164:167], v132 offset:1024
	ds_read_b128 v[168:171], v132 offset:2048
	ds_read_b128 v[172:175], v132 offset:3072
	v_add_u32_e32 v132, s68, v145
	ds_read_b128 v[176:179], v132
	ds_read_b128 v[180:183], v132 offset:1024
	ds_read_b128 v[184:187], v132 offset:2048
	ds_read_b128 v[188:191], v132 offset:3072
	v_lshl_add_u64 v[132:133], s[20:21], 0, v[156:157]
	s_add_i32 m0, s97, 0xc000
	ds_read_b128 v[192:195], v163
	ds_read_b128 v[196:199], v163 offset:1024
	ds_read_b128 v[214:217], v163 offset:2048
	ds_read_b128 v[218:221], v163 offset:3072
	ds_read_b128 v[222:225], v163 offset:4096
	ds_read_b128 v[226:229], v163 offset:5120
	ds_read_b128 v[230:233], v163 offset:6144
	ds_read_b128 v[234:237], v163 offset:7168
	global_load_lds_dwordx4 v[132:133], off
	v_lshl_add_u64 v[132:133], s[20:21], 0, v[154:155]
	s_add_i32 m0, s97, 0xe000
	s_nop 0
	global_load_lds_dwordx4 v[132:133], off
	s_waitcnt vmcnt(8)
	s_waitcnt lgkmcnt(0)
	s_barrier
	s_setprio 1
	v_mfma_f32_16x16x32_bf16 v[128:131], v[158:161], v[192:195], v[128:131]
	v_mfma_f32_16x16x32_bf16 v[124:127], v[168:171], v[192:195], v[124:127]
	v_mfma_f32_16x16x32_bf16 v[120:123], v[158:161], v[214:217], v[120:123]
	v_mfma_f32_16x16x32_bf16 v[112:115], v[168:171], v[214:217], v[112:115]
	v_mfma_f32_16x16x32_bf16 v[104:107], v[158:161], v[222:225], v[104:107]
	v_mfma_f32_16x16x32_bf16 v[96:99], v[168:171], v[222:225], v[96:99]
	v_mfma_f32_16x16x32_bf16 v[88:91], v[158:161], v[230:233], v[88:91]
	v_mfma_f32_16x16x32_bf16 v[80:83], v[168:171], v[230:233], v[80:83]
	v_mfma_f32_16x16x32_bf16 v[128:131], v[164:167], v[196:199], v[128:131]
	v_mfma_f32_16x16x32_bf16 v[124:127], v[172:175], v[196:199], v[124:127]
	v_mfma_f32_16x16x32_bf16 v[120:123], v[164:167], v[218:221], v[120:123]
	v_mfma_f32_16x16x32_bf16 v[112:115], v[172:175], v[218:221], v[112:115]
	v_mfma_f32_16x16x32_bf16 v[104:107], v[164:167], v[226:229], v[104:107]
	v_mfma_f32_16x16x32_bf16 v[96:99], v[172:175], v[226:229], v[96:99]
	v_mfma_f32_16x16x32_bf16 v[88:91], v[164:167], v[234:237], v[88:91]
	v_mfma_f32_16x16x32_bf16 v[80:83], v[172:175], v[234:237], v[80:83]
	v_mfma_f32_16x16x32_bf16 v[116:119], v[176:179], v[192:195], v[116:119]
	v_mfma_f32_16x16x32_bf16 v[108:111], v[184:187], v[192:195], v[108:111]
	v_mfma_f32_16x16x32_bf16 v[100:103], v[176:179], v[214:217], v[100:103]
	v_mfma_f32_16x16x32_bf16 v[92:95], v[184:187], v[214:217], v[92:95]
	v_mfma_f32_16x16x32_bf16 v[84:87], v[176:179], v[222:225], v[84:87]
	v_mfma_f32_16x16x32_bf16 v[76:79], v[184:187], v[222:225], v[76:79]
	v_mfma_f32_16x16x32_bf16 v[72:75], v[176:179], v[230:233], v[72:75]
	v_mfma_f32_16x16x32_bf16 v[68:71], v[184:187], v[230:233], v[68:71]
	v_mfma_f32_16x16x32_bf16 v[116:119], v[180:183], v[196:199], v[116:119]
	v_mfma_f32_16x16x32_bf16 v[108:111], v[188:191], v[196:199], v[108:111]
	v_mfma_f32_16x16x32_bf16 v[100:103], v[180:183], v[218:221], v[100:103]
	v_mfma_f32_16x16x32_bf16 v[92:95], v[188:191], v[218:221], v[92:95]
	v_mfma_f32_16x16x32_bf16 v[84:87], v[180:183], v[226:229], v[84:87]
	v_mfma_f32_16x16x32_bf16 v[76:79], v[188:191], v[226:229], v[76:79]
	v_mfma_f32_16x16x32_bf16 v[72:75], v[180:183], v[234:237], v[72:75]
	v_mfma_f32_16x16x32_bf16 v[68:71], v[188:191], v[234:237], v[68:71]
	s_setprio 0
	s_barrier
	s_add_i32 s43, s43, s95
	v_lshl_add_u64 v[132:133], s[24:25], 0, v[148:149]
	s_mov_b32 m0, s43
	ds_read_b128 v[192:195], v163 offset:16384
	ds_read_b128 v[196:199], v163 offset:17408
	ds_read_b128 v[214:217], v163 offset:18432
	ds_read_b128 v[218:221], v163 offset:19456
	ds_read_b128 v[222:225], v163 offset:20480
	ds_read_b128 v[226:229], v163 offset:21504
	ds_read_b128 v[230:233], v163 offset:22528
	ds_read_b128 v[234:237], v163 offset:23552
	global_load_lds_dwordx4 v[132:133], off
	s_add_i32 m0, s43, 0x2000
	s_add_u32 s86, s24, 0x40000
	v_lshl_add_u64 v[134:135], s[24:25], 0, v[0:1]
	s_addc_u32 s87, s25, 0
	s_add_i32 s43, s68, s95
	global_load_lds_dwordx4 v[134:135], off
	v_lshl_add_u64 v[140:141], s[86:87], 0, v[148:149]
	s_mov_b32 m0, s43
	v_lshl_add_u64 v[142:143], s[26:27], 0, v[146:147]
	global_load_lds_dwordx4 v[140:141], off
	v_lshl_add_u64 v[140:141], s[86:87], 0, v[0:1]
	s_add_i32 m0, s43, 0x2000
	s_nop 0
	global_load_lds_dwordx4 v[140:141], off
	v_lshl_add_u64 v[140:141], s[26:27], 0, v[150:151]
	s_mov_b32 m0, s97
	s_nop 0
	global_load_lds_dwordx4 v[140:141], off
	s_mov_b32 m0, s22
	s_nop 0
	global_load_lds_dwordx4 v[142:143], off
	s_waitcnt vmcnt(8)
	s_waitcnt lgkmcnt(0)
	s_barrier
; #define PG8_STAGE(bufoff, gbase, voff) do { _Pragma("unroll") for (int _i = 0; _i < 2; ++_i) \
;         __builtin_amdgcn_global_load_lds((const unsigned*)((const char*)(gbase) + (voff)[_i]), (LAS unsigned*)(lds + (bufoff) + ldsw + _i * 8192), 16, 0, 0); } while (0)
; #define PG8_LDA(dst, b, h) do { _Pragma("unroll") for (int m = 0; m < 4; ++m) _Pragma("unroll") for (int k = 0; k < 2; ++k) dst[m][k] = *(const LAS bf16x8*)(lds + PG8_SA(b, h) + aoff + m * 2048 + k * 1024); } while (0)
; #define PG8_LDB(dst, b, h) do { _Pragma("unroll") for (int n = 0; n < 2; ++n) _Pragma("unroll") for (int k = 0; k < 2; ++k) dst[n][k] = *(const LAS bf16x8*)(lds + PG8_SB(b, h) + boff + n * 2048 + k * 1024); } while (0)
; #define PG8_MMA(ai, bj, At, Bt) do { __builtin_amdgcn_s_setprio(1); _Pragma("unroll") for (int m = 0; m < 4; ++m) _Pragma("unroll") for (int n = 0; n < 2; ++n) _Pragma("unroll") for (int k = 0; k < 2; ++k) \
;         acc[ai][bj][m][n] = __builtin_amdgcn_mfma_f32_16x16x32_bf16(Bt[n][k], At[m][k], acc[ai][bj][m][n], 0, 0, 0); __builtin_amdgcn_s_setprio(0); } while (0)
; #define PG8_WAIT_V(n) asm volatile("s_waitcnt vmcnt(" #n ")" ::: "memory")
; #define PG8_WAIT_L(n) asm volatile("s_waitcnt lgkmcnt(" #n ")" ::: "memory")
; #define PG8_BAR __builtin_amdgcn_s_barrier()
; #define PG8_SCHED __builtin_amdgcn_sched_barrier(0)
; template <class Epi>
; __device__ __forceinline__ void gemm_phase(LAS unsigned char* lds, const Gemm g, const int G, const int cidx, const Epi& E) {
;     ...
;             PG8_WAIT_V(8); PG8_WAIT_L(0); PG8_BAR; PG8_MMA(1, 0, At, B0); PG8_MMA(1, 1, At, B1); PG8_BAR; PG8_SCHED;
;             PG8_LDB(B0, 1, 0); PG8_LDB(B1, 1, 1); PG8_SCHED; PG8_LDA(At, 1, 0); PG8_STAGE(PG8_SA(0, 1), a2 + hstep, voffA);
;             PG8_WAIT_V(8); PG8_WAIT_L(0); PG8_BAR; PG8_MMA(0, 0, At, B0); PG8_MMA(0, 1, At, B1); PG8_BAR; PG8_SCHED;
	s_setprio 1
	v_mfma_f32_16x16x32_bf16 v[64:67], v[158:161], v[192:195], v[64:67]
	v_mfma_f32_16x16x32_bf16 v[60:63], v[168:171], v[192:195], v[60:63]
	v_mfma_f32_16x16x32_bf16 v[56:59], v[158:161], v[214:217], v[56:59]
	v_mfma_f32_16x16x32_bf16 v[48:51], v[168:171], v[214:217], v[48:51]
	v_mfma_f32_16x16x32_bf16 v[40:43], v[158:161], v[222:225], v[40:43]
	v_mfma_f32_16x16x32_bf16 v[32:35], v[168:171], v[222:225], v[32:35]
	v_mfma_f32_16x16x32_bf16 v[24:27], v[158:161], v[230:233], v[24:27]
	v_mfma_f32_16x16x32_bf16 v[16:19], v[168:171], v[230:233], v[16:19]
	v_mfma_f32_16x16x32_bf16 v[64:67], v[164:167], v[196:199], v[64:67]
	v_mfma_f32_16x16x32_bf16 v[60:63], v[172:175], v[196:199], v[60:63]
	v_mfma_f32_16x16x32_bf16 v[56:59], v[164:167], v[218:221], v[56:59]
	v_mfma_f32_16x16x32_bf16 v[48:51], v[172:175], v[218:221], v[48:51]
	v_mfma_f32_16x16x32_bf16 v[40:43], v[164:167], v[226:229], v[40:43]
	v_mfma_f32_16x16x32_bf16 v[32:35], v[172:175], v[226:229], v[32:35]
	v_mfma_f32_16x16x32_bf16 v[24:27], v[164:167], v[234:237], v[24:27]
	v_mfma_f32_16x16x32_bf16 v[16:19], v[172:175], v[234:237], v[16:19]
	v_mfma_f32_16x16x32_bf16 v[52:55], v[176:179], v[192:195], v[52:55]
	v_mfma_f32_16x16x32_bf16 v[44:47], v[184:187], v[192:195], v[44:47]
	v_mfma_f32_16x16x32_bf16 v[36:39], v[176:179], v[214:217], v[36:39]
	v_mfma_f32_16x16x32_bf16 v[28:31], v[184:187], v[214:217], v[28:31]
	v_mfma_f32_16x16x32_bf16 v[20:23], v[176:179], v[222:225], v[20:23]
	v_mfma_f32_16x16x32_bf16 v[12:15], v[184:187], v[222:225], v[12:15]
	v_mfma_f32_16x16x32_bf16 v[8:11], v[176:179], v[230:233], v[8:11]
	v_mfma_f32_16x16x32_bf16 v[4:7], v[184:187], v[230:233], v[4:7]
	v_mfma_f32_16x16x32_bf16 v[52:55], v[180:183], v[196:199], v[52:55]
	v_mfma_f32_16x16x32_bf16 v[44:47], v[188:191], v[196:199], v[44:47]
	v_mfma_f32_16x16x32_bf16 v[36:39], v[180:183], v[218:221], v[36:39]
	v_mfma_f32_16x16x32_bf16 v[28:31], v[188:191], v[218:221], v[28:31]
	v_mfma_f32_16x16x32_bf16 v[20:23], v[180:183], v[226:229], v[20:23]
	v_mfma_f32_16x16x32_bf16 v[12:15], v[188:191], v[226:229], v[12:15]
	v_mfma_f32_16x16x32_bf16 v[8:11], v[180:183], v[234:237], v[8:11]
	v_mfma_f32_16x16x32_bf16 v[4:7], v[188:191], v[234:237], v[4:7]
	s_setprio 0
	s_barrier
	s_add_i32 s43, 0, 0x18000
	s_add_i32 s68, 0, 0x1c000
	v_add_u32_e32 v172, s43, v145
	v_add_u32_e32 v188, s68, v145
	ds_read_b128 v[158:161], v172
	ds_read_b128 v[164:167], v172 offset:1024
	ds_read_b128 v[168:171], v172 offset:2048
	ds_read_b128 v[172:175], v172 offset:3072
	ds_read_b128 v[176:179], v188
	ds_read_b128 v[180:183], v188 offset:1024
	ds_read_b128 v[184:187], v188 offset:2048
	ds_read_b128 v[188:191], v188 offset:3072
	s_add_u32 s26, s26, 0x40000
	s_addc_u32 s27, s27, 0
	s_mov_b32 m0, s16
	v_lshl_add_u64 v[200:201], s[26:27], 0, v[150:151]
	ds_read_b128 v[192:195], v163 offset:32768
	ds_read_b128 v[196:199], v163 offset:33792
	ds_read_b128 v[214:217], v163 offset:34816
	ds_read_b128 v[218:221], v163 offset:35840
	ds_read_b128 v[222:225], v163 offset:36864
	ds_read_b128 v[226:229], v163 offset:37888
	ds_read_b128 v[230:233], v163 offset:38912
	ds_read_b128 v[234:237], v163 offset:39936
	global_load_lds_dwordx4 v[200:201], off
	v_lshl_add_u64 v[200:201], s[26:27], 0, v[146:147]
	s_mov_b32 m0, s17
	s_nop 0
	global_load_lds_dwordx4 v[200:201], off
	s_waitcnt vmcnt(8)
	s_waitcnt lgkmcnt(0)
	s_barrier
	s_setprio 1
	v_mfma_f32_16x16x32_bf16 v[128:131], v[158:161], v[192:195], v[128:131]
	v_mfma_f32_16x16x32_bf16 v[124:127], v[168:171], v[192:195], v[124:127]
	v_mfma_f32_16x16x32_bf16 v[120:123], v[158:161], v[214:217], v[120:123]
	v_mfma_f32_16x16x32_bf16 v[112:115], v[168:171], v[214:217], v[112:115]
	v_mfma_f32_16x16x32_bf16 v[104:107], v[158:161], v[222:225], v[104:107]
	v_mfma_f32_16x16x32_bf16 v[96:99], v[168:171], v[222:225], v[96:99]
	v_mfma_f32_16x16x32_bf16 v[88:91], v[158:161], v[230:233], v[88:91]
	v_mfma_f32_16x16x32_bf16 v[80:83], v[168:171], v[230:233], v[80:83]
	v_mfma_f32_16x16x32_bf16 v[128:131], v[164:167], v[196:199], v[128:131]
	v_mfma_f32_16x16x32_bf16 v[124:127], v[172:175], v[196:199], v[124:127]
	v_mfma_f32_16x16x32_bf16 v[120:123], v[164:167], v[218:221], v[120:123]
	v_mfma_f32_16x16x32_bf16 v[112:115], v[172:175], v[218:221], v[112:115]
	v_mfma_f32_16x16x32_bf16 v[104:107], v[164:167], v[226:229], v[104:107]
	v_mfma_f32_16x16x32_bf16 v[96:99], v[172:175], v[226:229], v[96:99]
	v_mfma_f32_16x16x32_bf16 v[88:91], v[164:167], v[234:237], v[88:91]
	v_mfma_f32_16x16x32_bf16 v[80:83], v[172:175], v[234:237], v[80:83]
	v_mfma_f32_16x16x32_bf16 v[116:119], v[176:179], v[192:195], v[116:119]
	v_mfma_f32_16x16x32_bf16 v[108:111], v[184:187], v[192:195], v[108:111]
	v_mfma_f32_16x16x32_bf16 v[100:103], v[176:179], v[214:217], v[100:103]
	v_mfma_f32_16x16x32_bf16 v[92:95], v[184:187], v[214:217], v[92:95]
	v_mfma_f32_16x16x32_bf16 v[84:87], v[176:179], v[222:225], v[84:87]
	v_mfma_f32_16x16x32_bf16 v[76:79], v[184:187], v[222:225], v[76:79]
	v_mfma_f32_16x16x32_bf16 v[72:75], v[176:179], v[230:233], v[72:75]
	v_mfma_f32_16x16x32_bf16 v[68:71], v[184:187], v[230:233], v[68:71]
	v_mfma_f32_16x16x32_bf16 v[116:119], v[180:183], v[196:199], v[116:119]
	v_mfma_f32_16x16x32_bf16 v[108:111], v[188:191], v[196:199], v[108:111]
	v_mfma_f32_16x16x32_bf16 v[100:103], v[180:183], v[218:221], v[100:103]
	v_mfma_f32_16x16x32_bf16 v[92:95], v[188:191], v[218:221], v[92:95]
	v_mfma_f32_16x16x32_bf16 v[84:87], v[180:183], v[226:229], v[84:87]
	v_mfma_f32_16x16x32_bf16 v[76:79], v[188:191], v[226:229], v[76:79]
	v_mfma_f32_16x16x32_bf16 v[72:75], v[180:183], v[234:237], v[72:75]
	v_mfma_f32_16x16x32_bf16 v[68:71], v[188:191], v[234:237], v[68:71]
	s_setprio 0
	s_barrier
; #define PG8_STAGE(bufoff, gbase, voff) do { _Pragma("unroll") for (int _i = 0; _i < 2; ++_i) \
;         __builtin_amdgcn_global_load_lds((const unsigned*)((const char*)(gbase) + (voff)[_i]), (LAS unsigned*)(lds + (bufoff) + ldsw + _i * 8192), 16, 0, 0); } while (0)
; #define PG8_LDA(dst, b, h) do { _Pragma("unroll") for (int m = 0; m < 4; ++m) _Pragma("unroll") for (int k = 0; k < 2; ++k) dst[m][k] = *(const LAS bf16x8*)(lds + PG8_SA(b, h) + aoff + m * 2048 + k * 1024); } while (0)
; #define PG8_MMA(ai, bj, At, Bt) do { __builtin_amdgcn_s_setprio(1); _Pragma("unroll") for (int m = 0; m < 4; ++m) _Pragma("unroll") for (int n = 0; n < 2; ++n) _Pragma("unroll") for (int k = 0; k < 2; ++k) \
;         acc[ai][bj][m][n] = __builtin_amdgcn_mfma_f32_16x16x32_bf16(Bt[n][k], At[m][k], acc[ai][bj][m][n], 0, 0, 0); __builtin_amdgcn_s_setprio(0); } while (0)
; #define PG8_WAIT_V(n) asm volatile("s_waitcnt vmcnt(" #n ")" ::: "memory")
; #define PG8_WAIT_L(n) asm volatile("s_waitcnt lgkmcnt(" #n ")" ::: "memory")
; #define PG8_BAR __builtin_amdgcn_s_barrier()
; #define PG8_SCHED __builtin_amdgcn_sched_barrier(0)
;     __device__ __forceinline__ void operator()(const f32x4 (&acc)[2][2][4][2], const Unit& u, int wr, int wc, int fr, int fq) const {
;         if (u.pn < 11) {
; template <class Epi>
; __device__ __forceinline__ void gemm_phase(LAS unsigned char* lds, const Gemm g, const int G, const int cidx, const Epi& E) {
;     ...
;             PG8_LDA(At, 1, 1); PG8_STAGE(PG8_SB(1, 0), b3, voffB); PG8_STAGE(PG8_SB(1, 1), b3 + hstep, voffB); PG8_STAGE(PG8_SA(1, 0), a3, voffA);
;             PG8_WAIT_V(8); PG8_WAIT_L(0); PG8_BAR; PG8_MMA(1, 0, At, B0); PG8_MMA(1, 1, At, B1); PG8_BAR; PG8_SCHED;
;         }
	s_add_i32 s26, s43, s95
	v_lshl_add_u64 v[132:133], v[132:133], 0, s[46:47]
	s_mov_b32 m0, s26
	ds_read_b128 v[192:195], v163 offset:49152
	ds_read_b128 v[196:199], v163 offset:50176
	ds_read_b128 v[214:217], v163 offset:51200
	ds_read_b128 v[218:221], v163 offset:52224
	ds_read_b128 v[222:225], v163 offset:53248
	ds_read_b128 v[226:229], v163 offset:54272
	ds_read_b128 v[230:233], v163 offset:55296
	ds_read_b128 v[234:237], v163 offset:56320
	global_load_lds_dwordx4 v[132:133], off
	s_add_i32 m0, s26, 0x2000
	s_add_u32 s24, s24, 0x40080
	v_lshl_add_u64 v[132:133], v[134:135], 0, s[46:47]
	s_addc_u32 s25, s25, 0
	s_add_i32 s26, s68, s95
	global_load_lds_dwordx4 v[132:133], off
	v_lshl_add_u64 v[132:133], s[24:25], 0, v[148:149]
	s_mov_b32 m0, s26
	s_nop 0
	global_load_lds_dwordx4 v[132:133], off
	v_lshl_add_u64 v[132:133], s[24:25], 0, v[0:1]
	s_add_i32 m0, s26, 0x2000
	s_nop 0
	global_load_lds_dwordx4 v[132:133], off
	v_lshl_add_u64 v[132:133], v[140:141], 0, s[46:47]
	s_mov_b32 m0, s84
	s_nop 0
	global_load_lds_dwordx4 v[132:133], off
	v_lshl_add_u64 v[132:133], v[142:143], 0, s[46:47]
	s_mov_b32 m0, s76
	s_nop 0
	global_load_lds_dwordx4 v[132:133], off
	s_waitcnt vmcnt(8)
	s_waitcnt lgkmcnt(0)
	s_barrier
	s_setprio 1
	v_mfma_f32_16x16x32_bf16 v[64:67], v[158:161], v[192:195], v[64:67]
	v_mfma_f32_16x16x32_bf16 v[60:63], v[168:171], v[192:195], v[60:63]
	v_mfma_f32_16x16x32_bf16 v[56:59], v[158:161], v[214:217], v[56:59]
	v_mfma_f32_16x16x32_bf16 v[48:51], v[168:171], v[214:217], v[48:51]
	v_mfma_f32_16x16x32_bf16 v[40:43], v[158:161], v[222:225], v[40:43]
	v_mfma_f32_16x16x32_bf16 v[32:35], v[168:171], v[222:225], v[32:35]
	v_mfma_f32_16x16x32_bf16 v[24:27], v[158:161], v[230:233], v[24:27]
	v_mfma_f32_16x16x32_bf16 v[16:19], v[168:171], v[230:233], v[16:19]
	v_mfma_f32_16x16x32_bf16 v[64:67], v[164:167], v[196:199], v[64:67]
	v_mfma_f32_16x16x32_bf16 v[60:63], v[172:175], v[196:199], v[60:63]
	v_mfma_f32_16x16x32_bf16 v[56:59], v[164:167], v[218:221], v[56:59]
	v_mfma_f32_16x16x32_bf16 v[48:51], v[172:175], v[218:221], v[48:51]
	v_mfma_f32_16x16x32_bf16 v[40:43], v[164:167], v[226:229], v[40:43]
	v_mfma_f32_16x16x32_bf16 v[32:35], v[172:175], v[226:229], v[32:35]
	v_mfma_f32_16x16x32_bf16 v[24:27], v[164:167], v[234:237], v[24:27]
	v_mfma_f32_16x16x32_bf16 v[16:19], v[172:175], v[234:237], v[16:19]
	v_mfma_f32_16x16x32_bf16 v[52:55], v[176:179], v[192:195], v[52:55]
	v_mfma_f32_16x16x32_bf16 v[44:47], v[184:187], v[192:195], v[44:47]
	v_mfma_f32_16x16x32_bf16 v[36:39], v[176:179], v[214:217], v[36:39]
	v_mfma_f32_16x16x32_bf16 v[28:31], v[184:187], v[214:217], v[28:31]
	v_mfma_f32_16x16x32_bf16 v[20:23], v[176:179], v[222:225], v[20:23]
	v_mfma_f32_16x16x32_bf16 v[12:15], v[184:187], v[222:225], v[12:15]
	v_mfma_f32_16x16x32_bf16 v[8:11], v[176:179], v[230:233], v[8:11]
	v_mfma_f32_16x16x32_bf16 v[4:7], v[184:187], v[230:233], v[4:7]
	v_mfma_f32_16x16x32_bf16 v[52:55], v[180:183], v[196:199], v[52:55]
	v_mfma_f32_16x16x32_bf16 v[44:47], v[188:191], v[196:199], v[44:47]
	v_mfma_f32_16x16x32_bf16 v[36:39], v[180:183], v[218:221], v[36:39]
	v_mfma_f32_16x16x32_bf16 v[28:31], v[188:191], v[218:221], v[28:31]
	v_mfma_f32_16x16x32_bf16 v[20:23], v[180:183], v[226:229], v[20:23]
	v_mfma_f32_16x16x32_bf16 v[12:15], v[188:191], v[226:229], v[12:15]
	v_mfma_f32_16x16x32_bf16 v[8:11], v[180:183], v[234:237], v[8:11]
	v_mfma_f32_16x16x32_bf16 v[4:7], v[188:191], v[234:237], v[4:7]
	s_setprio 0
	s_barrier
	s_add_i32 s45, s45, 2
	s_add_u32 s42, s42, 0x100
	s_addc_u32 s44, s44, 0
	s_add_u32 s20, s20, 0x100
	s_addc_u32 s21, s21, 0
	s_cmp_gt_u32 s45, 13
	s_cbranch_scc0 .LBB0_601
	s_cmp_gt_i32 s35, 10
	s_mov_b64 s[20:21], -1
	s_mov_b32 s26, 0x1a000
	s_mov_b32 s27, 0x19000
	s_cbranch_scc0 .LBB0_604
; __device__ __forceinline__ unsigned pk2(float lo, float hi) { unsigned r; asm("v_cvt_pk_bf16_f32 %0, %1, %2" : "=v"(r) : "v"(lo), "v"(hi)); return r; }
;     __device__ __forceinline__ void operator()(const f32x4 (&acc)[2][2][4][2], const Unit& u, int wr, int wc, int fr, int fq) const {
;     ...
;             const int g = u.pn - 11, n = g >> 2, q = g & 3;
;             bf16_t* blk = Gt + (((size_t)n * 64 + u.pm) * 8 + q * 2) * 32768 + (size_t)((wr * 4 * 4 + wc) * 64 + fq * 16 + fr) * 8;
; #pragma unroll
;             for (int ai = 0; ai < 2; ++ai)
; #pragma unroll
;                 for (int m = 0; m < 4; ++m)
; #pragma unroll
;                     for (int bj = 0; bj < 2; ++bj) { const f32x4 v0 = acc[ai][bj][m][0], v1 = acc[ai][bj][m][1];
;                         u32x4 w; w.x = pk2(v0[0], v0[1]); w.y = pk2(v0[2], v0[3]); w.z = pk2(v1[0], v1[1]); w.w = pk2(v1[2], v1[3]);
;                         *(u32x4*)(blk + (size_t)bj * 32768 + (size_t)((ai * 8 + m) * 4) * 512) = w; }
	s_add_i32 s9, s35, -11
	s_mov_b32 s21, s77
	s_lshr_b32 s20, s9, 2
	s_ashr_i32 s19, s18, 31
	s_lshl_b64 s[20:21], s[20:21], 9
	s_lshl_b64 s[24:25], s[18:19], 3
	s_add_u32 s11, s20, s24
	s_addc_u32 s21, s21, s25
	s_lshl_b32 s9, s9, 1
	s_and_b32 s9, s9, 6
	s_or_b32 s20, s11, s9
	s_lshl_b64 s[20:21], s[20:21], 16
	v_lshl_add_u64 v[158:159], v[152:153], 0, s[20:21]
	s_mov_b32 s9, 0x11000
	v_add_co_u32_e32 v132, vcc, s9, v158
	v_cvt_pk_bf16_f32 v164, v128, v129
	v_cvt_pk_bf16_f32 v165, v130, v131
	v_cvt_pk_bf16_f32 v166, v124, v125
	v_cvt_pk_bf16_f32 v167, v126, v127
	s_nop 1
	v_addc_co_u32_e32 v133, vcc, 0, v159, vcc
	global_store_dwordx4 v[158:159], v[164:167], off
	v_add_co_u32_e32 v134, vcc, s81, v158
	s_nop 0
	v_cvt_pk_bf16_f32 v164, v116, v117
	v_cvt_pk_bf16_f32 v165, v118, v119
	v_cvt_pk_bf16_f32 v166, v108, v109
	v_cvt_pk_bf16_f32 v167, v110, v111
	global_store_dwordx4 v[132:133], v[164:167], off offset:-4096
	v_addc_co_u32_e32 v135, vcc, 0, v159, vcc
	s_nop 0
	v_cvt_pk_bf16_f32 v164, v120, v121
	v_cvt_pk_bf16_f32 v165, v122, v123
	v_cvt_pk_bf16_f32 v166, v112, v113
	v_cvt_pk_bf16_f32 v167, v114, v115
	s_mov_b32 s9, 0x13000
	global_store_dwordx4 v[134:135], v[164:167], off offset:-4096
	s_mov_b64 s[20:21], 0
	s_nop 0
	v_cvt_pk_bf16_f32 v164, v100, v101
	v_cvt_pk_bf16_f32 v165, v102, v103
	v_cvt_pk_bf16_f32 v166, v92, v93
	v_cvt_pk_bf16_f32 v167, v94, v95
	global_store_dwordx4 v[132:133], v[164:167], off
	v_add_co_u32_e32 v132, vcc, s9, v158
	s_nop 0
	v_cvt_pk_bf16_f32 v164, v104, v105
	v_cvt_pk_bf16_f32 v165, v106, v107
	v_cvt_pk_bf16_f32 v166, v96, v97
	v_cvt_pk_bf16_f32 v167, v98, v99
	s_nop 0
	v_addc_co_u32_e32 v133, vcc, 0, v159, vcc
	global_store_dwordx4 v[134:135], v[164:167], off
	v_add_co_u32_e32 v134, vcc, s82, v158
	s_nop 0
	v_cvt_pk_bf16_f32 v164, v84, v85
	v_cvt_pk_bf16_f32 v165, v86, v87
	v_cvt_pk_bf16_f32 v166, v76, v77
	v_cvt_pk_bf16_f32 v167, v78, v79
	global_store_dwordx4 v[132:133], v[164:167], off offset:-4096
	v_addc_co_u32_e32 v135, vcc, 0, v159, vcc
	s_nop 0
	v_cvt_pk_bf16_f32 v164, v88, v89
	v_cvt_pk_bf16_f32 v165, v90, v91
	v_cvt_pk_bf16_f32 v166, v80, v81
	v_cvt_pk_bf16_f32 v167, v82, v83
	s_mov_b32 s9, 0x9000
	global_store_dwordx4 v[134:135], v[164:167], off
	s_nop 1
	v_cvt_pk_bf16_f32 v164, v72, v73
	v_cvt_pk_bf16_f32 v165, v74, v75
	v_cvt_pk_bf16_f32 v166, v68, v69
	v_cvt_pk_bf16_f32 v167, v70, v71
	global_store_dwordx4 v[132:133], v[164:167], off
	v_add_co_u32_e32 v132, vcc, s9, v158
	s_nop 0
	v_cvt_pk_bf16_f32 v164, v64, v65
	v_cvt_pk_bf16_f32 v165, v66, v67
	v_cvt_pk_bf16_f32 v166, v60, v61
	v_cvt_pk_bf16_f32 v167, v62, v63
	s_nop 0
	v_addc_co_u32_e32 v133, vcc, 0, v159, vcc
	v_add_co_u32_e32 v134, vcc, s27, v158
	global_store_dwordx4 v[132:133], v[164:167], off offset:-4096
	s_nop 0
	v_addc_co_u32_e32 v135, vcc, 0, v159, vcc
	v_cvt_pk_bf16_f32 v164, v52, v53
	v_cvt_pk_bf16_f32 v165, v54, v55
	v_cvt_pk_bf16_f32 v166, v44, v45
	v_cvt_pk_bf16_f32 v167, v46, v47
	s_mov_b32 s9, 0xb000
	global_store_dwordx4 v[134:135], v[164:167], off offset:-4096
	s_nop 1
	v_cvt_pk_bf16_f32 v164, v56, v57
	v_cvt_pk_bf16_f32 v165, v58, v59
	v_cvt_pk_bf16_f32 v166, v48, v49
	v_cvt_pk_bf16_f32 v167, v50, v51
	global_store_dwordx4 v[132:133], v[164:167], off
	v_add_co_u32_e32 v132, vcc, s9, v158
	s_nop 0
	v_cvt_pk_bf16_f32 v164, v36, v37
	v_cvt_pk_bf16_f32 v165, v38, v39
	v_cvt_pk_bf16_f32 v166, v28, v29
	v_cvt_pk_bf16_f32 v167, v30, v31
	s_nop 0
	v_addc_co_u32_e32 v133, vcc, 0, v159, vcc
	global_store_dwordx4 v[134:135], v[164:167], off
	v_add_co_u32_e32 v134, vcc, s26, v158
	s_nop 0
	v_cvt_pk_bf16_f32 v164, v40, v41
	v_cvt_pk_bf16_f32 v165, v42, v43
	v_cvt_pk_bf16_f32 v166, v32, v33
	v_cvt_pk_bf16_f32 v167, v34, v35
	global_store_dwordx4 v[132:133], v[164:167], off offset:-4096
	v_addc_co_u32_e32 v135, vcc, 0, v159, vcc
	s_nop 0
	v_cvt_pk_bf16_f32 v164, v20, v21
	v_cvt_pk_bf16_f32 v165, v22, v23
	v_cvt_pk_bf16_f32 v166, v12, v13
	v_cvt_pk_bf16_f32 v167, v14, v15
	global_store_dwordx4 v[134:135], v[164:167], off
	s_nop 1
	v_cvt_pk_bf16_f32 v164, v24, v25
	v_cvt_pk_bf16_f32 v165, v26, v27
	v_cvt_pk_bf16_f32 v166, v16, v17
	v_cvt_pk_bf16_f32 v167, v18, v19
	global_store_dwordx4 v[132:133], v[164:167], off
	v_add_co_u32_e32 v132, vcc, 0x1b000, v158
	s_nop 0
	v_cvt_pk_bf16_f32 v164, v8, v9
	v_cvt_pk_bf16_f32 v165, v10, v11
	v_cvt_pk_bf16_f32 v166, v4, v5
	v_cvt_pk_bf16_f32 v167, v6, v7
	s_nop 0
	v_addc_co_u32_e32 v133, vcc, 0, v159, vcc
	global_store_dwordx4 v[132:133], v[164:167], off
